# speedup vs baseline: 1.0334x; 1.0026x over previous
; __device__ __forceinline__ unsigned cvt_pk_bf16(float lo, float hi) { unsigned r; asm volatile("v_cvt_pk_bf16_f32 %0, %1, %2" : "=v"(r) : "v"(lo), "v"(hi)); return r; }
; __device__ __forceinline__ void unpack8(const v4u q, float (&f)[8]) { f[0] = bflo(q.x); f[1] = bfhi(q.x); f[2] = bflo(q.y); f[3] = bfhi(q.y); f[4] = bflo(q.z); f[5] = bfhi(q.z); f[6] = bflo(q.w); f[7] = bfhi(q.w); }
;     __device__ __forceinline__ void operator()(const f32x4 (&acc)[2][2][4][2], const Unit& u, int wr, int wc, int fr, int fq) const {
;         const int row0 = u.pm * 256 + wr * 64 + fr, c = u.pn * 256 + wc * 64 + 8 * fq;
; #pragma unroll
;         for (int ai = 0; ai < 2; ++ai)
; #pragma unroll
;             for (int m = 0; m < 4; ++m) {
;                 const int row = row0 + ai * 128 + m * 16; float ss = 0.f;
; #pragma unroll
;                 for (int bj = 0; bj < 2; ++bj) {
;                     const size_t off = (size_t)row * D + c + bj * 32;
;                     float xo[8]; unpack8(*(const v4u*)(xb + off), xo);
;                     const f32x4 a0 = acc[ai][bj][m][0], a1 = acc[ai][bj][m][1];
;                     const f32x4 y0 = {xo[0] + a0[0], xo[1] + a0[1], xo[2] + a0[2], xo[3] + a0[3]}, y1 = {xo[4] + a1[0], xo[5] + a1[1], xo[6] + a1[2], xo[7] + a1[3]};
;                     v4u w; w.x = pg8::cvt_pk_bf16(y0[0], y0[1]); w.y = pg8::cvt_pk_bf16(y0[2], y0[3]); w.z = pg8::cvt_pk_bf16(y1[0], y1[1]); w.w = pg8::cvt_pk_bf16(y1[2], y1[3]);
;                     *(v4u*)(xb + off) = w;
;                     ss += (y0[0] * y0[0] + y0[1] * y0[1]) + (y0[2] * y0[2] + y0[3] * y0[3]) + (y1[0] * y1[0] + y1[1] * y1[1]) + (y1[2] * y1[2] + y1[3] * y1[3]);
;                 }
;                 ss += __shfl_xor(ss, 16); ss += __shfl_xor(ss, 32);
;                 if (fq == 0) ssq[(size_t)(u.pn * 4 + wc) * T + row] = ss;
;             }
.LBB0_49:
	s_lshl_b32 s0, s17, 8
	s_add_i32 s0, s0, s56
	v_and_or_b32 v0, v219, 15, s0
	s_lshl_b32 s0, s16, 8
	v_lshrrev_b32_e32 v1, 1, v219
	s_or_b32 s0, s0, s58
	v_and_b32_e32 v1, 56, v1
	v_add_u32_e32 v134, s0, v1
	s_lshl_b32 s0, s16, 2
	s_or_b32 s16, s0, s55
	v_ashrrev_i32_e32 v1, 31, v0
	v_readlane_b32 s0, v254, 41
	v_lshlrev_b64 v[132:133], 11, v[0:1]
	v_readlane_b32 s1, v254, 42
	v_ashrrev_i32_e32 v135, 31, v134
	v_cmp_lt_i32_e32 vcc, v225, v220
	v_lshl_add_u64 v[132:133], s[0:1], 0, v[132:133]
	v_lshl_add_u64 v[132:133], v[134:135], 1, v[132:133]
	v_lshlrev_b32_e32 v147, 1, v134
	v_lshl_add_u32 v147, v0, 11, v147
	global_load_dwordx4 v[148:151], v147, s[0:1]
	global_load_dwordx4 v[152:155], v147, s[0:1] offset:64
	v_add_u32_e32 v234, 0x8000, v147
	global_load_dwordx4 v[156:159], v234, s[0:1]
	global_load_dwordx4 v[160:163], v234, s[0:1] offset:64
	v_add_u32_e32 v234, 0x10000, v147
	global_load_dwordx4 v[164:167], v234, s[0:1]
	global_load_dwordx4 v[168:171], v234, s[0:1] offset:64
	v_add_u32_e32 v234, 0x18000, v147
	global_load_dwordx4 v[172:175], v234, s[0:1]
	global_load_dwordx4 v[176:179], v234, s[0:1] offset:64
	v_add_u32_e32 v234, 0x40000, v147
	global_load_dwordx4 v[180:183], v234, s[0:1]
	global_load_dwordx4 v[184:187], v234, s[0:1] offset:64
	v_add_u32_e32 v234, 0x48000, v147
	global_load_dwordx4 v[188:191], v234, s[0:1]
	global_load_dwordx4 v[196:199], v234, s[0:1] offset:64
	v_add_u32_e32 v234, 0x50000, v147
	global_load_dwordx4 v[200:203], v234, s[0:1]
	global_load_dwordx4 v[204:207], v234, s[0:1] offset:64
	v_add_u32_e32 v234, 0x58000, v147
	global_load_dwordx4 v[208:211], v234, s[0:1]
	global_load_dwordx4 v[212:215], v234, s[0:1] offset:64
	s_waitcnt vmcnt(0)
	v_mov_b64_e32 v[140:141], v[148:149]
	v_mov_b64_e32 v[142:143], v[150:151]
	s_ashr_i32 s17, s16, 31
	v_cmp_gt_u32_e64 s[40:41], 16, v219
	s_lshl_b64 s[42:43], s[16:17], 17
	v_lshlrev_b32_e32 v139, 16, v140
	v_and_b32_e32 v140, 0xffff0000, v140
	v_lshlrev_b32_e32 v144, 16, v141
	v_and_b32_e32 v141, 0xffff0000, v141
	v_lshlrev_b32_e32 v145, 16, v142
	v_and_b32_e32 v142, 0xffff0000, v142
	v_lshlrev_b32_e32 v146, 16, v143
	v_and_b32_e32 v143, 0xffff0000, v143
	v_add_f32_e32 v128, v128, v139
	v_add_f32_e32 v129, v129, v140
	v_add_f32_e32 v130, v130, v144
	v_add_f32_e32 v131, v131, v141
	v_add_f32_e32 v139, v124, v145
	v_add_f32_e32 v140, v125, v142
	v_cvt_pk_bf16_f32 v124, v128, v129
	v_cvt_pk_bf16_f32 v125, v130, v131
	v_add_f32_e32 v141, v126, v146
	v_add_f32_e32 v142, v127, v143
	v_cvt_pk_bf16_f32 v126, v139, v140
	v_cvt_pk_bf16_f32 v127, v141, v142
	global_store_dwordx4 v[132:133], v[124:127], off
	s_nop 1
	v_mul_f32_e32 v124, v129, v129
	v_mul_f32_e32 v125, v131, v131
	v_fmac_f32_e32 v124, v128, v128
	v_fmac_f32_e32 v125, v130, v130
	v_add_f32_e32 v124, v124, v125
	v_mul_f32_e32 v125, v140, v140
	v_fmac_f32_e32 v125, v139, v139
	v_add_f32_e32 v124, v125, v124
	v_mul_f32_e32 v125, v142, v142
	v_fmac_f32_e32 v125, v141, v141
	v_add_f32_e32 v128, v125, v124
	v_mov_b64_e32 v[124:125], v[152:153]
	v_mov_b64_e32 v[126:127], v[154:155]
	v_lshlrev_b32_e32 v129, 16, v124
	v_and_b32_e32 v124, 0xffff0000, v124
	v_lshlrev_b32_e32 v130, 16, v125
	v_and_b32_e32 v125, 0xffff0000, v125
	v_lshlrev_b32_e32 v131, 16, v126
	v_and_b32_e32 v126, 0xffff0000, v126
	v_lshlrev_b32_e32 v139, 16, v127
	v_and_b32_e32 v127, 0xffff0000, v127
	v_add_f32_e32 v120, v120, v129
	v_add_f32_e32 v121, v121, v124
	v_add_f32_e32 v122, v122, v130
	v_add_f32_e32 v123, v123, v125
	v_add_f32_e32 v124, v116, v131
	v_add_f32_e32 v125, v117, v126
	v_cvt_pk_bf16_f32 v116, v120, v121
	v_cvt_pk_bf16_f32 v117, v122, v123
	v_add_f32_e32 v126, v118, v139
	v_add_f32_e32 v127, v119, v127
	v_cvt_pk_bf16_f32 v118, v124, v125
	v_cvt_pk_bf16_f32 v119, v126, v127
	global_store_dwordx4 v[132:133], v[116:119], off offset:64
	s_nop 1
	v_mul_f32_e32 v116, v121, v121
	v_mul_f32_e32 v117, v123, v123
	v_fmac_f32_e32 v116, v120, v120
	v_fmac_f32_e32 v117, v122, v122
	v_add_f32_e32 v116, v116, v117
	v_mul_f32_e32 v117, v125, v125
	v_fmac_f32_e32 v117, v124, v124
	v_add_f32_e32 v116, v117, v116
	v_mul_f32_e32 v117, v127, v127
	v_fmac_f32_e32 v117, v126, v126
	v_add_f32_e32 v116, v117, v116
	v_add_f32_e32 v117, v128, v116
	v_cndmask_b32_e32 v116, v219, v225, vcc
	v_lshlrev_b32_e32 v116, 2, v116
	ds_bpermute_b32 v118, v116, v117
	v_cmp_lt_i32_e32 vcc, v226, v220
	s_waitcnt lgkmcnt(0)
	v_add_f32_e32 v118, v117, v118
	v_cndmask_b32_e32 v117, v219, v226, vcc
	v_lshlrev_b32_e32 v117, 2, v117
	ds_bpermute_b32 v119, v117, v118
	s_and_saveexec_b64 s[46:47], s[40:41]
	s_cbranch_execz .LBB0_51
	s_add_u32 s16, s84, s42
	s_addc_u32 s17, s85, s43
	s_waitcnt lgkmcnt(0)
	v_add_f32_e32 v120, v118, v119
	v_lshl_add_u64 v[118:119], v[0:1], 2, s[16:17]
	global_store_dword v[118:119], v120, off
; __device__ __forceinline__ unsigned cvt_pk_bf16(float lo, float hi) { unsigned r; asm volatile("v_cvt_pk_bf16_f32 %0, %1, %2" : "=v"(r) : "v"(lo), "v"(hi)); return r; }
; __device__ __forceinline__ void unpack8(const v4u q, float (&f)[8]) { f[0] = bflo(q.x); f[1] = bfhi(q.x); f[2] = bflo(q.y); f[3] = bfhi(q.y); f[4] = bflo(q.z); f[5] = bfhi(q.z); f[6] = bflo(q.w); f[7] = bfhi(q.w); }
;     __device__ __forceinline__ void operator()(const f32x4 (&acc)[2][2][4][2], const Unit& u, int wr, int wc, int fr, int fq) const {
;         const int row0 = u.pm * 256 + wr * 64 + fr, c = u.pn * 256 + wc * 64 + 8 * fq;
; #pragma unroll
;         for (int ai = 0; ai < 2; ++ai)
; #pragma unroll
;             for (int m = 0; m < 4; ++m) {
;                 const int row = row0 + ai * 128 + m * 16; float ss = 0.f;
; #pragma unroll
;                 for (int bj = 0; bj < 2; ++bj) {
;                     const size_t off = (size_t)row * D + c + bj * 32;
;                     float xo[8]; unpack8(*(const v4u*)(xb + off), xo);
;                     const f32x4 a0 = acc[ai][bj][m][0], a1 = acc[ai][bj][m][1];
;                     const f32x4 y0 = {xo[0] + a0[0], xo[1] + a0[1], xo[2] + a0[2], xo[3] + a0[3]}, y1 = {xo[4] + a1[0], xo[5] + a1[1], xo[6] + a1[2], xo[7] + a1[3]};
;                     v4u w; w.x = pg8::cvt_pk_bf16(y0[0], y0[1]); w.y = pg8::cvt_pk_bf16(y0[2], y0[3]); w.z = pg8::cvt_pk_bf16(y1[0], y1[1]); w.w = pg8::cvt_pk_bf16(y1[2], y1[3]);
;                     *(v4u*)(xb + off) = w;
;                     ss += (y0[0] * y0[0] + y0[1] * y0[1]) + (y0[2] * y0[2] + y0[3] * y0[3]) + (y1[0] * y1[0] + y1[1] * y1[1]) + (y1[2] * y1[2] + y1[3] * y1[3]);
;                 }
;                 ss += __shfl_xor(ss, 16); ss += __shfl_xor(ss, 32);
;                 if (fq == 0) ssq[(size_t)(u.pn * 4 + wc) * T + row] = ss;
;             }
.LBB0_51:
	s_or_b64 exec, exec, s[46:47]
	v_or_b32_e32 v118, 16, v0
	s_waitcnt lgkmcnt(0)
	v_ashrrev_i32_e32 v119, 31, v118
	v_readlane_b32 s0, v254, 41
	v_lshlrev_b64 v[118:119], 11, v[118:119]
	v_readlane_b32 s1, v254, 42
	s_nop 1
	v_lshl_add_u64 v[118:119], s[0:1], 0, v[118:119]
	v_lshl_add_u64 v[122:123], v[134:135], 1, v[118:119]
	v_mov_b64_e32 v[118:119], v[156:157]
	v_mov_b64_e32 v[120:121], v[158:159]
	v_lshlrev_b32_e32 v124, 16, v118
	v_and_b32_e32 v118, 0xffff0000, v118
	v_lshlrev_b32_e32 v125, 16, v119
	v_and_b32_e32 v119, 0xffff0000, v119
	v_lshlrev_b32_e32 v126, 16, v120
	v_and_b32_e32 v120, 0xffff0000, v120
	v_lshlrev_b32_e32 v127, 16, v121
	v_and_b32_e32 v121, 0xffff0000, v121
	v_add_f32_e32 v124, v112, v124
	v_add_f32_e32 v118, v113, v118
	v_add_f32_e32 v125, v114, v125
	v_add_f32_e32 v119, v115, v119
	v_add_f32_e32 v126, v108, v126
	v_add_f32_e32 v120, v109, v120
	v_add_f32_e32 v127, v110, v127
	v_add_f32_e32 v121, v111, v121
	v_cvt_pk_bf16_f32 v108, v124, v118
	v_cvt_pk_bf16_f32 v109, v125, v119
	v_cvt_pk_bf16_f32 v110, v126, v120
	v_cvt_pk_bf16_f32 v111, v127, v121
	v_mov_b64_e32 v[112:113], v[160:161]
	v_mov_b64_e32 v[114:115], v[162:163]
	v_mul_f32_e32 v118, v118, v118
	v_mul_f32_e32 v119, v119, v119
	v_mul_f32_e32 v120, v120, v120
	v_fmac_f32_e32 v118, v124, v124
	v_fmac_f32_e32 v119, v125, v125
	v_mul_f32_e32 v121, v121, v121
	v_fmac_f32_e32 v120, v126, v126
	v_add_f32_e32 v118, v118, v119
	v_fmac_f32_e32 v121, v127, v127
	v_add_f32_e32 v118, v120, v118
	v_add_f32_e32 v118, v121, v118
	global_store_dwordx4 v[122:123], v[108:111], off
	v_lshlrev_b32_e32 v119, 16, v112
	v_and_b32_e32 v112, 0xffff0000, v112
	v_lshlrev_b32_e32 v120, 16, v113
	v_and_b32_e32 v113, 0xffff0000, v113
	v_lshlrev_b32_e32 v121, 16, v114
	v_and_b32_e32 v114, 0xffff0000, v114
	v_add_f32_e32 v105, v105, v112
	v_add_f32_e32 v107, v107, v113
	v_lshlrev_b32_e32 v124, 16, v115
	v_and_b32_e32 v115, 0xffff0000, v115
	v_add_f32_e32 v104, v104, v119
	v_add_f32_e32 v106, v106, v120
	v_add_f32_e32 v112, v100, v121
	v_add_f32_e32 v113, v101, v114
	v_mul_f32_e32 v100, v105, v105
	v_mul_f32_e32 v101, v107, v107
	v_add_f32_e32 v114, v102, v124
	v_add_f32_e32 v115, v103, v115
	v_mul_f32_e32 v102, v113, v113
	v_fmac_f32_e32 v100, v104, v104
	v_fmac_f32_e32 v101, v106, v106
	v_mul_f32_e32 v103, v115, v115
	v_fmac_f32_e32 v102, v112, v112
	v_add_f32_e32 v100, v100, v101
	v_add_f32_e32 v100, v102, v100
	v_fmac_f32_e32 v103, v114, v114
	v_add_f32_e32 v100, v103, v100
	v_add_f32_e32 v100, v118, v100
	ds_bpermute_b32 v101, v116, v100
	v_cvt_pk_bf16_f32 v102, v104, v105
	v_cvt_pk_bf16_f32 v103, v106, v107
	v_cvt_pk_bf16_f32 v104, v112, v113
	v_cvt_pk_bf16_f32 v105, v114, v115
	s_waitcnt lgkmcnt(0)
	v_add_f32_e32 v100, v100, v101
	ds_bpermute_b32 v101, v117, v100
	global_store_dwordx4 v[122:123], v[102:105], off offset:64
	s_and_saveexec_b64 s[46:47], s[40:41]
	s_cbranch_execz .LBB0_53
	s_add_u32 s16, s84, s42
	s_addc_u32 s17, s85, s43
	s_waitcnt lgkmcnt(0)
	v_add_f32_e32 v102, v100, v101
	v_lshl_add_u64 v[100:101], v[0:1], 2, s[16:17]
	global_store_dword v[100:101], v102, off offset:64
.LBB0_53:
	s_or_b64 exec, exec, s[46:47]
	v_or_b32_e32 v100, 32, v0
	s_waitcnt lgkmcnt(0)
	v_ashrrev_i32_e32 v101, 31, v100
	v_readlane_b32 s0, v254, 41
	v_lshlrev_b64 v[100:101], 11, v[100:101]
	v_readlane_b32 s1, v254, 42
	s_nop 1
	v_lshl_add_u64 v[100:101], s[0:1], 0, v[100:101]
	v_lshl_add_u64 v[104:105], v[134:135], 1, v[100:101]
	v_mov_b64_e32 v[100:101], v[164:165]
	v_mov_b64_e32 v[102:103], v[166:167]
	v_lshlrev_b32_e32 v106, 16, v100
	v_and_b32_e32 v100, 0xffff0000, v100
	v_lshlrev_b32_e32 v107, 16, v101
	v_and_b32_e32 v101, 0xffff0000, v101
	v_lshlrev_b32_e32 v108, 16, v102
	v_and_b32_e32 v102, 0xffff0000, v102
	v_lshlrev_b32_e32 v109, 16, v103
	v_and_b32_e32 v103, 0xffff0000, v103
	v_add_f32_e32 v106, v96, v106
	v_add_f32_e32 v100, v97, v100
	v_add_f32_e32 v107, v98, v107
	v_add_f32_e32 v101, v99, v101
	v_add_f32_e32 v108, v92, v108
	v_add_f32_e32 v102, v93, v102
	v_add_f32_e32 v109, v94, v109
	v_add_f32_e32 v103, v95, v103
	v_cvt_pk_bf16_f32 v92, v106, v100
	v_cvt_pk_bf16_f32 v93, v107, v101
	v_cvt_pk_bf16_f32 v94, v108, v102
	v_cvt_pk_bf16_f32 v95, v109, v103
	v_mov_b64_e32 v[96:97], v[168:169]
	v_mov_b64_e32 v[98:99], v[170:171]
	v_mul_f32_e32 v100, v100, v100
	v_mul_f32_e32 v101, v101, v101
	v_mul_f32_e32 v102, v102, v102
	v_fmac_f32_e32 v100, v106, v106
	v_fmac_f32_e32 v101, v107, v107
	v_mul_f32_e32 v103, v103, v103
	v_fmac_f32_e32 v102, v108, v108
	v_add_f32_e32 v100, v100, v101
	v_fmac_f32_e32 v103, v109, v109
	v_add_f32_e32 v100, v102, v100
	v_add_f32_e32 v100, v103, v100
	global_store_dwordx4 v[104:105], v[92:95], off
	v_lshlrev_b32_e32 v101, 16, v96
	v_and_b32_e32 v96, 0xffff0000, v96
	v_lshlrev_b32_e32 v102, 16, v97
	v_and_b32_e32 v97, 0xffff0000, v97
	v_lshlrev_b32_e32 v103, 16, v98
	v_and_b32_e32 v98, 0xffff0000, v98
	v_add_f32_e32 v89, v89, v96
	v_add_f32_e32 v91, v91, v97
	v_lshlrev_b32_e32 v106, 16, v99
	v_and_b32_e32 v99, 0xffff0000, v99
	v_add_f32_e32 v88, v88, v101
	v_add_f32_e32 v90, v90, v102
	v_add_f32_e32 v96, v84, v103
	v_add_f32_e32 v97, v85, v98
	v_mul_f32_e32 v84, v89, v89
	v_mul_f32_e32 v85, v91, v91
	v_add_f32_e32 v98, v86, v106
	v_add_f32_e32 v99, v87, v99
	v_mul_f32_e32 v86, v97, v97
	v_fmac_f32_e32 v84, v88, v88
	v_fmac_f32_e32 v85, v90, v90
	v_mul_f32_e32 v87, v99, v99
	v_fmac_f32_e32 v86, v96, v96
	v_add_f32_e32 v84, v84, v85
	v_add_f32_e32 v84, v86, v84
	v_fmac_f32_e32 v87, v98, v98
	v_add_f32_e32 v84, v87, v84
	v_add_f32_e32 v84, v100, v84
	ds_bpermute_b32 v85, v116, v84
	v_cvt_pk_bf16_f32 v86, v88, v89
	v_cvt_pk_bf16_f32 v87, v90, v91
	v_cvt_pk_bf16_f32 v88, v96, v97
	v_cvt_pk_bf16_f32 v89, v98, v99
	s_waitcnt lgkmcnt(0)
	v_add_f32_e32 v84, v84, v85
	ds_bpermute_b32 v85, v117, v84
	global_store_dwordx4 v[104:105], v[86:89], off offset:64
	s_and_saveexec_b64 s[46:47], s[40:41]
	s_cbranch_execz .LBB0_55
	s_add_u32 s16, s84, s42
	s_addc_u32 s17, s85, s43
	s_waitcnt lgkmcnt(0)
	v_add_f32_e32 v86, v84, v85
	v_lshl_add_u64 v[84:85], v[0:1], 2, s[16:17]
	global_store_dword v[84:85], v86, off offset:128
; __device__ __forceinline__ unsigned cvt_pk_bf16(float lo, float hi) { unsigned r; asm volatile("v_cvt_pk_bf16_f32 %0, %1, %2" : "=v"(r) : "v"(lo), "v"(hi)); return r; }
; __device__ __forceinline__ void unpack8(const v4u q, float (&f)[8]) { f[0] = bflo(q.x); f[1] = bfhi(q.x); f[2] = bflo(q.y); f[3] = bfhi(q.y); f[4] = bflo(q.z); f[5] = bfhi(q.z); f[6] = bflo(q.w); f[7] = bfhi(q.w); }
;     __device__ __forceinline__ void operator()(const f32x4 (&acc)[2][2][4][2], const Unit& u, int wr, int wc, int fr, int fq) const {
;         const int row0 = u.pm * 256 + wr * 64 + fr, c = u.pn * 256 + wc * 64 + 8 * fq;
; #pragma unroll
;         for (int ai = 0; ai < 2; ++ai)
; #pragma unroll
;             for (int m = 0; m < 4; ++m) {
;                 const int row = row0 + ai * 128 + m * 16; float ss = 0.f;
; #pragma unroll
;                 for (int bj = 0; bj < 2; ++bj) {
;                     const size_t off = (size_t)row * D + c + bj * 32;
;                     float xo[8]; unpack8(*(const v4u*)(xb + off), xo);
;                     const f32x4 a0 = acc[ai][bj][m][0], a1 = acc[ai][bj][m][1];
;                     const f32x4 y0 = {xo[0] + a0[0], xo[1] + a0[1], xo[2] + a0[2], xo[3] + a0[3]}, y1 = {xo[4] + a1[0], xo[5] + a1[1], xo[6] + a1[2], xo[7] + a1[3]};
;                     v4u w; w.x = pg8::cvt_pk_bf16(y0[0], y0[1]); w.y = pg8::cvt_pk_bf16(y0[2], y0[3]); w.z = pg8::cvt_pk_bf16(y1[0], y1[1]); w.w = pg8::cvt_pk_bf16(y1[2], y1[3]);
;                     *(v4u*)(xb + off) = w;
;                     ss += (y0[0] * y0[0] + y0[1] * y0[1]) + (y0[2] * y0[2] + y0[3] * y0[3]) + (y1[0] * y1[0] + y1[1] * y1[1]) + (y1[2] * y1[2] + y1[3] * y1[3]);
;                 }
;                 ss += __shfl_xor(ss, 16); ss += __shfl_xor(ss, 32);
;                 if (fq == 0) ssq[(size_t)(u.pn * 4 + wc) * T + row] = ss;
;             }
.LBB0_55:
	s_or_b64 exec, exec, s[46:47]
	v_or_b32_e32 v84, 48, v0
	s_waitcnt lgkmcnt(0)
	v_ashrrev_i32_e32 v85, 31, v84
	v_readlane_b32 s0, v254, 41
	v_lshlrev_b64 v[84:85], 11, v[84:85]
	v_readlane_b32 s1, v254, 42
	s_nop 1
	v_lshl_add_u64 v[84:85], s[0:1], 0, v[84:85]
	v_lshl_add_u64 v[88:89], v[134:135], 1, v[84:85]
	v_mov_b64_e32 v[84:85], v[172:173]
	v_mov_b64_e32 v[86:87], v[174:175]
	v_lshlrev_b32_e32 v90, 16, v84
	v_and_b32_e32 v84, 0xffff0000, v84
	v_lshlrev_b32_e32 v91, 16, v85
	v_and_b32_e32 v85, 0xffff0000, v85
	v_lshlrev_b32_e32 v92, 16, v86
	v_and_b32_e32 v86, 0xffff0000, v86
	v_lshlrev_b32_e32 v93, 16, v87
	v_and_b32_e32 v87, 0xffff0000, v87
	v_add_f32_e32 v90, v80, v90
	v_add_f32_e32 v84, v81, v84
	v_add_f32_e32 v91, v82, v91
	v_add_f32_e32 v85, v83, v85
	v_add_f32_e32 v92, v76, v92
	v_add_f32_e32 v86, v77, v86
	v_add_f32_e32 v93, v78, v93
	v_add_f32_e32 v87, v79, v87
	v_cvt_pk_bf16_f32 v76, v90, v84
	v_cvt_pk_bf16_f32 v77, v91, v85
	v_cvt_pk_bf16_f32 v78, v92, v86
	v_cvt_pk_bf16_f32 v79, v93, v87
	v_mov_b64_e32 v[80:81], v[176:177]
	v_mov_b64_e32 v[82:83], v[178:179]
	v_mul_f32_e32 v84, v84, v84
	v_mul_f32_e32 v85, v85, v85
	v_mul_f32_e32 v86, v86, v86
	v_fmac_f32_e32 v84, v90, v90
	v_fmac_f32_e32 v85, v91, v91
	v_mul_f32_e32 v87, v87, v87
	v_fmac_f32_e32 v86, v92, v92
	v_add_f32_e32 v84, v84, v85
	v_fmac_f32_e32 v87, v93, v93
	v_add_f32_e32 v84, v86, v84
	v_add_f32_e32 v84, v87, v84
	global_store_dwordx4 v[88:89], v[76:79], off
	v_lshlrev_b32_e32 v85, 16, v80
	v_and_b32_e32 v80, 0xffff0000, v80
	v_lshlrev_b32_e32 v86, 16, v81
	v_and_b32_e32 v81, 0xffff0000, v81
	v_lshlrev_b32_e32 v87, 16, v82
	v_and_b32_e32 v82, 0xffff0000, v82
	v_add_f32_e32 v73, v73, v80
	v_add_f32_e32 v75, v75, v81
	v_lshlrev_b32_e32 v90, 16, v83
	v_and_b32_e32 v83, 0xffff0000, v83
	v_add_f32_e32 v72, v72, v85
	v_add_f32_e32 v74, v74, v86
	v_add_f32_e32 v80, v68, v87
	v_add_f32_e32 v81, v69, v82
	v_mul_f32_e32 v68, v73, v73
	v_mul_f32_e32 v69, v75, v75
	v_add_f32_e32 v82, v70, v90
	v_add_f32_e32 v83, v71, v83
	v_mul_f32_e32 v70, v81, v81
	v_fmac_f32_e32 v68, v72, v72
	v_fmac_f32_e32 v69, v74, v74
	v_mul_f32_e32 v71, v83, v83
	v_fmac_f32_e32 v70, v80, v80
	v_add_f32_e32 v68, v68, v69
	v_add_f32_e32 v68, v70, v68
	v_fmac_f32_e32 v71, v82, v82
	v_add_f32_e32 v68, v71, v68
	v_add_f32_e32 v68, v84, v68
	ds_bpermute_b32 v69, v116, v68
	v_cvt_pk_bf16_f32 v70, v72, v73
	v_cvt_pk_bf16_f32 v71, v74, v75
	v_cvt_pk_bf16_f32 v72, v80, v81
	v_cvt_pk_bf16_f32 v73, v82, v83
	s_waitcnt lgkmcnt(0)
	v_add_f32_e32 v68, v68, v69
	ds_bpermute_b32 v69, v117, v68
	global_store_dwordx4 v[88:89], v[70:73], off offset:64
	s_and_saveexec_b64 s[46:47], s[40:41]
	s_cbranch_execz .LBB0_57
	s_add_u32 s16, s84, s42
	s_addc_u32 s17, s85, s43
	s_waitcnt lgkmcnt(0)
	v_add_f32_e32 v70, v68, v69
	v_lshl_add_u64 v[68:69], v[0:1], 2, s[16:17]
	global_store_dword v[68:69], v70, off offset:192
.LBB0_57:
	s_or_b64 exec, exec, s[46:47]
	v_add_co_u32_e32 v72, vcc, 0x40000, v132
	s_mov_b64 s[0:1], 0x40000
	s_nop 0
	v_addc_co_u32_e32 v73, vcc, 0, v133, vcc
	s_waitcnt lgkmcnt(0)
	v_mov_b64_e32 v[68:69], v[180:181]
	v_mov_b64_e32 v[70:71], v[182:183]
	v_lshl_add_u64 v[74:75], v[132:133], 0, s[0:1]
	v_lshlrev_b32_e32 v76, 16, v68
	v_and_b32_e32 v68, 0xffff0000, v68
	v_lshlrev_b32_e32 v77, 16, v69
	v_and_b32_e32 v69, 0xffff0000, v69
	v_lshlrev_b32_e32 v78, 16, v70
	v_and_b32_e32 v70, 0xffff0000, v70
	v_lshlrev_b32_e32 v79, 16, v71
	v_and_b32_e32 v71, 0xffff0000, v71
	v_add_f32_e32 v76, v64, v76
	v_add_f32_e32 v68, v65, v68
	v_add_f32_e32 v77, v66, v77
	v_add_f32_e32 v69, v67, v69
	v_add_f32_e32 v78, v60, v78
	v_add_f32_e32 v70, v61, v70
	v_add_f32_e32 v79, v62, v79
	v_add_f32_e32 v71, v63, v71
	v_cvt_pk_bf16_f32 v60, v76, v68
	v_cvt_pk_bf16_f32 v61, v77, v69
	v_cvt_pk_bf16_f32 v62, v78, v70
	v_cvt_pk_bf16_f32 v63, v79, v71
	v_mov_b64_e32 v[64:65], v[184:185]
	v_mov_b64_e32 v[66:67], v[186:187]
	v_mul_f32_e32 v68, v68, v68
	v_mul_f32_e32 v69, v69, v69
	v_mul_f32_e32 v70, v70, v70
	v_fmac_f32_e32 v68, v76, v76
	v_fmac_f32_e32 v69, v77, v77
	v_mul_f32_e32 v71, v71, v71
	v_fmac_f32_e32 v70, v78, v78
	v_add_f32_e32 v68, v68, v69
	v_fmac_f32_e32 v71, v79, v79
	v_add_f32_e32 v68, v70, v68
	v_add_f32_e32 v68, v71, v68
	global_store_dwordx4 v[72:73], v[60:63], off
	v_lshlrev_b32_e32 v69, 16, v64
	v_and_b32_e32 v64, 0xffff0000, v64
	v_lshlrev_b32_e32 v70, 16, v65
	v_and_b32_e32 v65, 0xffff0000, v65
	v_lshlrev_b32_e32 v71, 16, v66
	v_and_b32_e32 v66, 0xffff0000, v66
	v_add_f32_e32 v57, v57, v64
	v_add_f32_e32 v59, v59, v65
	v_lshlrev_b32_e32 v76, 16, v67
	v_and_b32_e32 v67, 0xffff0000, v67
	v_add_f32_e32 v56, v56, v69
	v_add_f32_e32 v58, v58, v70
	v_add_f32_e32 v64, v52, v71
	v_add_f32_e32 v65, v53, v66
	v_mul_f32_e32 v52, v57, v57
	v_mul_f32_e32 v53, v59, v59
	v_add_f32_e32 v66, v54, v76
	v_add_f32_e32 v67, v55, v67
	v_mul_f32_e32 v54, v65, v65
	v_fmac_f32_e32 v52, v56, v56
	v_fmac_f32_e32 v53, v58, v58
	v_mul_f32_e32 v55, v67, v67
	v_fmac_f32_e32 v54, v64, v64
	v_add_f32_e32 v52, v52, v53
	v_add_f32_e32 v52, v54, v52
	v_fmac_f32_e32 v55, v66, v66
	v_add_f32_e32 v52, v55, v52
	v_add_f32_e32 v52, v68, v52
	ds_bpermute_b32 v53, v116, v52
	v_cvt_pk_bf16_f32 v54, v56, v57
	v_cvt_pk_bf16_f32 v55, v58, v59
	v_cvt_pk_bf16_f32 v56, v64, v65
	v_cvt_pk_bf16_f32 v57, v66, v67
	s_waitcnt lgkmcnt(0)
	v_add_f32_e32 v52, v52, v53
	ds_bpermute_b32 v53, v117, v52
	global_store_dwordx4 v[74:75], v[54:57], off offset:64
	s_and_saveexec_b64 s[46:47], s[40:41]
	s_cbranch_execz .LBB0_59
	s_add_u32 s16, s84, s42
	s_addc_u32 s17, s85, s43
	s_waitcnt lgkmcnt(0)
	v_add_f32_e32 v54, v52, v53
	v_lshl_add_u64 v[52:53], v[0:1], 2, s[16:17]
	global_store_dword v[52:53], v54, off offset:512
; __device__ __forceinline__ unsigned cvt_pk_bf16(float lo, float hi) { unsigned r; asm volatile("v_cvt_pk_bf16_f32 %0, %1, %2" : "=v"(r) : "v"(lo), "v"(hi)); return r; }
; __device__ __forceinline__ void unpack8(const v4u q, float (&f)[8]) { f[0] = bflo(q.x); f[1] = bfhi(q.x); f[2] = bflo(q.y); f[3] = bfhi(q.y); f[4] = bflo(q.z); f[5] = bfhi(q.z); f[6] = bflo(q.w); f[7] = bfhi(q.w); }
;     __device__ __forceinline__ void operator()(const f32x4 (&acc)[2][2][4][2], const Unit& u, int wr, int wc, int fr, int fq) const {
;         const int row0 = u.pm * 256 + wr * 64 + fr, c = u.pn * 256 + wc * 64 + 8 * fq;
; #pragma unroll
;         for (int ai = 0; ai < 2; ++ai)
; #pragma unroll
;             for (int m = 0; m < 4; ++m) {
;                 const int row = row0 + ai * 128 + m * 16; float ss = 0.f;
; #pragma unroll
;                 for (int bj = 0; bj < 2; ++bj) {
;                     const size_t off = (size_t)row * D + c + bj * 32;
;                     float xo[8]; unpack8(*(const v4u*)(xb + off), xo);
;                     const f32x4 a0 = acc[ai][bj][m][0], a1 = acc[ai][bj][m][1];
;                     const f32x4 y0 = {xo[0] + a0[0], xo[1] + a0[1], xo[2] + a0[2], xo[3] + a0[3]}, y1 = {xo[4] + a1[0], xo[5] + a1[1], xo[6] + a1[2], xo[7] + a1[3]};
;                     v4u w; w.x = pg8::cvt_pk_bf16(y0[0], y0[1]); w.y = pg8::cvt_pk_bf16(y0[2], y0[3]); w.z = pg8::cvt_pk_bf16(y1[0], y1[1]); w.w = pg8::cvt_pk_bf16(y1[2], y1[3]);
;                     *(v4u*)(xb + off) = w;
;                     ss += (y0[0] * y0[0] + y0[1] * y0[1]) + (y0[2] * y0[2] + y0[3] * y0[3]) + (y1[0] * y1[0] + y1[1] * y1[1]) + (y1[2] * y1[2] + y1[3] * y1[3]);
;                 }
;                 ss += __shfl_xor(ss, 16); ss += __shfl_xor(ss, 32);
;                 if (fq == 0) ssq[(size_t)(u.pn * 4 + wc) * T + row] = ss;
;             }
.LBB0_59:
	s_or_b64 exec, exec, s[46:47]
	v_add_co_u32_e32 v56, vcc, 0x48000, v132
	s_mov_b64 s[0:1], 0x48000
	s_nop 0
	v_addc_co_u32_e32 v57, vcc, 0, v133, vcc
	s_waitcnt lgkmcnt(0)
	v_mov_b64_e32 v[52:53], v[188:189]
	v_mov_b64_e32 v[54:55], v[190:191]
	v_lshl_add_u64 v[58:59], v[132:133], 0, s[0:1]
	v_lshlrev_b32_e32 v60, 16, v52
	v_and_b32_e32 v52, 0xffff0000, v52
	v_lshlrev_b32_e32 v61, 16, v53
	v_and_b32_e32 v53, 0xffff0000, v53
	v_lshlrev_b32_e32 v62, 16, v54
	v_and_b32_e32 v54, 0xffff0000, v54
	v_lshlrev_b32_e32 v63, 16, v55
	v_and_b32_e32 v55, 0xffff0000, v55
	v_add_f32_e32 v60, v48, v60
	v_add_f32_e32 v52, v49, v52
	v_add_f32_e32 v61, v50, v61
	v_add_f32_e32 v53, v51, v53
	v_add_f32_e32 v62, v44, v62
	v_add_f32_e32 v54, v45, v54
	v_add_f32_e32 v63, v46, v63
	v_add_f32_e32 v55, v47, v55
	v_cvt_pk_bf16_f32 v44, v60, v52
	v_cvt_pk_bf16_f32 v45, v61, v53
	v_cvt_pk_bf16_f32 v46, v62, v54
	v_cvt_pk_bf16_f32 v47, v63, v55
	v_mov_b64_e32 v[48:49], v[196:197]
	v_mov_b64_e32 v[50:51], v[198:199]
	v_mul_f32_e32 v52, v52, v52
	v_mul_f32_e32 v53, v53, v53
	v_mul_f32_e32 v54, v54, v54
	v_fmac_f32_e32 v52, v60, v60
	v_fmac_f32_e32 v53, v61, v61
	v_mul_f32_e32 v55, v55, v55
	v_fmac_f32_e32 v54, v62, v62
	v_add_f32_e32 v52, v52, v53
	v_fmac_f32_e32 v55, v63, v63
	v_add_f32_e32 v52, v54, v52
	v_add_f32_e32 v52, v55, v52
	global_store_dwordx4 v[56:57], v[44:47], off
	v_lshlrev_b32_e32 v53, 16, v48
	v_and_b32_e32 v48, 0xffff0000, v48
	v_lshlrev_b32_e32 v54, 16, v49
	v_and_b32_e32 v49, 0xffff0000, v49
	v_lshlrev_b32_e32 v55, 16, v50
	v_and_b32_e32 v50, 0xffff0000, v50
	v_add_f32_e32 v41, v41, v48
	v_add_f32_e32 v43, v43, v49
	v_lshlrev_b32_e32 v60, 16, v51
	v_and_b32_e32 v51, 0xffff0000, v51
	v_add_f32_e32 v40, v40, v53
	v_add_f32_e32 v42, v42, v54
	v_add_f32_e32 v48, v36, v55
	v_add_f32_e32 v49, v37, v50
	v_mul_f32_e32 v36, v41, v41
	v_mul_f32_e32 v37, v43, v43
	v_add_f32_e32 v50, v38, v60
	v_add_f32_e32 v51, v39, v51
	v_mul_f32_e32 v38, v49, v49
	v_fmac_f32_e32 v36, v40, v40
	v_fmac_f32_e32 v37, v42, v42
	v_mul_f32_e32 v39, v51, v51
	v_fmac_f32_e32 v38, v48, v48
	v_add_f32_e32 v36, v36, v37
	v_add_f32_e32 v36, v38, v36
	v_fmac_f32_e32 v39, v50, v50
	v_add_f32_e32 v36, v39, v36
	v_add_f32_e32 v36, v52, v36
	ds_bpermute_b32 v37, v116, v36
	v_cvt_pk_bf16_f32 v38, v40, v41
	v_cvt_pk_bf16_f32 v39, v42, v43
	v_cvt_pk_bf16_f32 v40, v48, v49
	v_cvt_pk_bf16_f32 v41, v50, v51
	s_waitcnt lgkmcnt(0)
	v_add_f32_e32 v36, v36, v37
	ds_bpermute_b32 v37, v117, v36
	global_store_dwordx4 v[58:59], v[38:41], off offset:64
	s_and_saveexec_b64 s[46:47], s[40:41]
	s_cbranch_execz .LBB0_61
	s_add_u32 s16, s84, s42
	s_addc_u32 s17, s85, s43
	s_waitcnt lgkmcnt(0)
	v_add_f32_e32 v38, v36, v37
	v_lshl_add_u64 v[36:37], v[0:1], 2, s[16:17]
	global_store_dword v[36:37], v38, off offset:576
; __device__ __forceinline__ unsigned cvt_pk_bf16(float lo, float hi) { unsigned r; asm volatile("v_cvt_pk_bf16_f32 %0, %1, %2" : "=v"(r) : "v"(lo), "v"(hi)); return r; }
; __device__ __forceinline__ void unpack8(const v4u q, float (&f)[8]) { f[0] = bflo(q.x); f[1] = bfhi(q.x); f[2] = bflo(q.y); f[3] = bfhi(q.y); f[4] = bflo(q.z); f[5] = bfhi(q.z); f[6] = bflo(q.w); f[7] = bfhi(q.w); }
;     __device__ __forceinline__ void operator()(const f32x4 (&acc)[2][2][4][2], const Unit& u, int wr, int wc, int fr, int fq) const {
;         const int row0 = u.pm * 256 + wr * 64 + fr, c = u.pn * 256 + wc * 64 + 8 * fq;
; #pragma unroll
;         for (int ai = 0; ai < 2; ++ai)
; #pragma unroll
;             for (int m = 0; m < 4; ++m) {
;                 const int row = row0 + ai * 128 + m * 16; float ss = 0.f;
; #pragma unroll
;                 for (int bj = 0; bj < 2; ++bj) {
;                     const size_t off = (size_t)row * D + c + bj * 32;
;                     float xo[8]; unpack8(*(const v4u*)(xb + off), xo);
;                     const f32x4 a0 = acc[ai][bj][m][0], a1 = acc[ai][bj][m][1];
;                     const f32x4 y0 = {xo[0] + a0[0], xo[1] + a0[1], xo[2] + a0[2], xo[3] + a0[3]}, y1 = {xo[4] + a1[0], xo[5] + a1[1], xo[6] + a1[2], xo[7] + a1[3]};
;                     v4u w; w.x = pg8::cvt_pk_bf16(y0[0], y0[1]); w.y = pg8::cvt_pk_bf16(y0[2], y0[3]); w.z = pg8::cvt_pk_bf16(y1[0], y1[1]); w.w = pg8::cvt_pk_bf16(y1[2], y1[3]);
;                     *(v4u*)(xb + off) = w;
;                     ss += (y0[0] * y0[0] + y0[1] * y0[1]) + (y0[2] * y0[2] + y0[3] * y0[3]) + (y1[0] * y1[0] + y1[1] * y1[1]) + (y1[2] * y1[2] + y1[3] * y1[3]);
;                 }
;                 ss += __shfl_xor(ss, 16); ss += __shfl_xor(ss, 32);
;                 if (fq == 0) ssq[(size_t)(u.pn * 4 + wc) * T + row] = ss;
;             }
.LBB0_61:
	s_or_b64 exec, exec, s[46:47]
	v_add_co_u32_e32 v40, vcc, 0x50000, v132
	s_mov_b64 s[0:1], 0x50000
	s_nop 0
	v_addc_co_u32_e32 v41, vcc, 0, v133, vcc
	s_waitcnt lgkmcnt(0)
	v_mov_b64_e32 v[36:37], v[200:201]
	v_mov_b64_e32 v[38:39], v[202:203]
	v_lshl_add_u64 v[42:43], v[132:133], 0, s[0:1]
	v_lshlrev_b32_e32 v44, 16, v36
	v_and_b32_e32 v36, 0xffff0000, v36
	v_lshlrev_b32_e32 v45, 16, v37
	v_and_b32_e32 v37, 0xffff0000, v37
	v_lshlrev_b32_e32 v46, 16, v38
	v_and_b32_e32 v38, 0xffff0000, v38
	v_lshlrev_b32_e32 v47, 16, v39
	v_and_b32_e32 v39, 0xffff0000, v39
	v_add_f32_e32 v44, v32, v44
	v_add_f32_e32 v36, v33, v36
	v_add_f32_e32 v45, v34, v45
	v_add_f32_e32 v37, v35, v37
	v_add_f32_e32 v46, v28, v46
	v_add_f32_e32 v38, v29, v38
	v_add_f32_e32 v47, v30, v47
	v_add_f32_e32 v39, v31, v39
	v_cvt_pk_bf16_f32 v28, v44, v36
	v_cvt_pk_bf16_f32 v29, v45, v37
	v_cvt_pk_bf16_f32 v30, v46, v38
	v_cvt_pk_bf16_f32 v31, v47, v39
	v_mov_b64_e32 v[32:33], v[204:205]
	v_mov_b64_e32 v[34:35], v[206:207]
	v_mul_f32_e32 v36, v36, v36
	v_mul_f32_e32 v37, v37, v37
	v_mul_f32_e32 v38, v38, v38
	v_fmac_f32_e32 v36, v44, v44
	v_fmac_f32_e32 v37, v45, v45
	v_mul_f32_e32 v39, v39, v39
	v_fmac_f32_e32 v38, v46, v46
	v_add_f32_e32 v36, v36, v37
	v_fmac_f32_e32 v39, v47, v47
	v_add_f32_e32 v36, v38, v36
	v_add_f32_e32 v36, v39, v36
	global_store_dwordx4 v[40:41], v[28:31], off
	v_lshlrev_b32_e32 v37, 16, v32
	v_and_b32_e32 v32, 0xffff0000, v32
	v_lshlrev_b32_e32 v38, 16, v33
	v_and_b32_e32 v33, 0xffff0000, v33
	v_lshlrev_b32_e32 v39, 16, v34
	v_and_b32_e32 v34, 0xffff0000, v34
	v_add_f32_e32 v25, v25, v32
	v_add_f32_e32 v27, v27, v33
	v_lshlrev_b32_e32 v44, 16, v35
	v_and_b32_e32 v35, 0xffff0000, v35
	v_add_f32_e32 v24, v24, v37
	v_add_f32_e32 v26, v26, v38
	v_add_f32_e32 v32, v20, v39
	v_add_f32_e32 v33, v21, v34
	v_mul_f32_e32 v20, v25, v25
	v_mul_f32_e32 v21, v27, v27
	v_add_f32_e32 v34, v22, v44
	v_add_f32_e32 v35, v23, v35
	v_mul_f32_e32 v22, v33, v33
	v_fmac_f32_e32 v20, v24, v24
	v_fmac_f32_e32 v21, v26, v26
	v_mul_f32_e32 v23, v35, v35
	v_fmac_f32_e32 v22, v32, v32
	v_add_f32_e32 v20, v20, v21
	v_add_f32_e32 v20, v22, v20
	v_fmac_f32_e32 v23, v34, v34
	v_add_f32_e32 v20, v23, v20
	v_add_f32_e32 v20, v36, v20
	ds_bpermute_b32 v21, v116, v20
	v_cvt_pk_bf16_f32 v22, v24, v25
	v_cvt_pk_bf16_f32 v23, v26, v27
	v_cvt_pk_bf16_f32 v24, v32, v33
	v_cvt_pk_bf16_f32 v25, v34, v35
	s_waitcnt lgkmcnt(0)
	v_add_f32_e32 v20, v20, v21
	ds_bpermute_b32 v21, v117, v20
	global_store_dwordx4 v[42:43], v[22:25], off offset:64
	s_and_saveexec_b64 s[46:47], s[40:41]
	s_cbranch_execz .LBB0_63
	s_add_u32 s16, s84, s42
	s_addc_u32 s17, s85, s43
	s_waitcnt lgkmcnt(0)
	v_add_f32_e32 v22, v20, v21
	v_lshl_add_u64 v[20:21], v[0:1], 2, s[16:17]
	global_store_dword v[20:21], v22, off offset:640
.LBB0_63:
	s_or_b64 exec, exec, s[46:47]
	v_add_co_u32_e32 v26, vcc, 0x58000, v132
	s_mov_b64 s[0:1], 0x58000
	s_nop 0
	v_addc_co_u32_e32 v27, vcc, 0, v133, vcc
	s_waitcnt lgkmcnt(0)
	v_mov_b64_e32 v[20:21], v[208:209]
	v_mov_b64_e32 v[22:23], v[210:211]
	v_lshl_add_u64 v[24:25], v[132:133], 0, s[0:1]
	v_lshlrev_b32_e32 v28, 16, v20
	v_and_b32_e32 v20, 0xffff0000, v20
	v_lshlrev_b32_e32 v29, 16, v21
	v_and_b32_e32 v21, 0xffff0000, v21
	v_lshlrev_b32_e32 v30, 16, v22
	v_and_b32_e32 v22, 0xffff0000, v22
	v_lshlrev_b32_e32 v31, 16, v23
	v_and_b32_e32 v23, 0xffff0000, v23
	v_add_f32_e32 v16, v16, v28
	v_add_f32_e32 v17, v17, v20
	v_add_f32_e32 v18, v18, v29
	v_add_f32_e32 v19, v19, v21
	v_add_f32_e32 v20, v12, v30
	v_add_f32_e32 v21, v13, v22
	v_cvt_pk_bf16_f32 v12, v16, v17
	v_cvt_pk_bf16_f32 v13, v18, v19
	v_add_f32_e32 v22, v14, v31
	v_add_f32_e32 v23, v15, v23
	v_cvt_pk_bf16_f32 v14, v20, v21
	v_cvt_pk_bf16_f32 v15, v22, v23
	global_store_dwordx4 v[26:27], v[12:15], off
	s_nop 1
	v_mul_f32_e32 v12, v17, v17
	v_mul_f32_e32 v13, v19, v19
	v_fmac_f32_e32 v12, v16, v16
	v_fmac_f32_e32 v13, v18, v18
	v_add_f32_e32 v12, v12, v13
	v_mul_f32_e32 v13, v21, v21
	v_fmac_f32_e32 v13, v20, v20
	v_add_f32_e32 v12, v13, v12
	v_mul_f32_e32 v13, v23, v23
	v_fmac_f32_e32 v13, v22, v22
	v_add_f32_e32 v16, v13, v12
	v_mov_b64_e32 v[12:13], v[212:213]
	v_mov_b64_e32 v[14:15], v[214:215]
	v_lshlrev_b32_e32 v17, 16, v12
	v_and_b32_e32 v12, 0xffff0000, v12
	v_lshlrev_b32_e32 v18, 16, v13
	v_and_b32_e32 v13, 0xffff0000, v13
	v_lshlrev_b32_e32 v19, 16, v14
	v_and_b32_e32 v14, 0xffff0000, v14
	v_lshlrev_b32_e32 v20, 16, v15
	v_and_b32_e32 v15, 0xffff0000, v15
	v_add_f32_e32 v8, v8, v17
	v_add_f32_e32 v9, v9, v12
	v_add_f32_e32 v10, v10, v18
	v_add_f32_e32 v11, v11, v13
	v_add_f32_e32 v12, v4, v19
	v_add_f32_e32 v13, v5, v14
	v_cvt_pk_bf16_f32 v4, v8, v9
	v_cvt_pk_bf16_f32 v5, v10, v11
	v_add_f32_e32 v14, v6, v20
	v_add_f32_e32 v15, v7, v15
	v_cvt_pk_bf16_f32 v6, v12, v13
	v_cvt_pk_bf16_f32 v7, v14, v15
	global_store_dwordx4 v[24:25], v[4:7], off offset:64
	s_nop 1
	v_mul_f32_e32 v4, v9, v9
	v_mul_f32_e32 v5, v11, v11
	v_fmac_f32_e32 v4, v8, v8
	v_fmac_f32_e32 v5, v10, v10
	v_add_f32_e32 v4, v4, v5
	v_mul_f32_e32 v5, v13, v13
	v_fmac_f32_e32 v5, v12, v12
	v_add_f32_e32 v4, v5, v4
	v_mul_f32_e32 v5, v15, v15
	v_fmac_f32_e32 v5, v14, v14
	v_add_f32_e32 v4, v5, v4
	v_add_f32_e32 v4, v16, v4
	ds_bpermute_b32 v5, v116, v4
	s_waitcnt lgkmcnt(0)
	v_add_f32_e32 v4, v4, v5
	ds_bpermute_b32 v5, v117, v4
	s_and_saveexec_b64 s[46:47], s[40:41]
	s_cbranch_execz .LBB0_65
	s_add_u32 s16, s84, s42
	s_addc_u32 s17, s85, s43
	s_waitcnt lgkmcnt(0)
	v_add_f32_e32 v4, v4, v5
	v_lshl_add_u64 v[0:1], v[0:1], 2, s[16:17]
	global_store_dword v[0:1], v4, off offset:704

; __device__ __forceinline__ unsigned cvt_pk_bf16(float lo, float hi) { unsigned r; asm volatile("v_cvt_pk_bf16_f32 %0, %1, %2" : "=v"(r) : "v"(lo), "v"(hi)); return r; }
; __device__ __forceinline__ void unpack8(const v4u q, float (&f)[8]) { f[0] = bflo(q.x); f[1] = bfhi(q.x); f[2] = bflo(q.y); f[3] = bfhi(q.y); f[4] = bflo(q.z); f[5] = bfhi(q.z); f[6] = bflo(q.w); f[7] = bfhi(q.w); }
;     __device__ __forceinline__ void operator()(const f32x4 (&acc)[2][2][4][2], const Unit& u, int wr, int wc, int fr, int fq) const {
;         const int row0 = u.pm * 256 + wr * 64 + fr, c = u.pn * 256 + wc * 64 + 8 * fq;
; #pragma unroll
;         for (int ai = 0; ai < 2; ++ai)
; #pragma unroll
;             for (int m = 0; m < 4; ++m) {
;                 const int row = row0 + ai * 128 + m * 16; float ss = 0.f;
; #pragma unroll
;                 for (int bj = 0; bj < 2; ++bj) {
;                     const size_t off = (size_t)row * D + c + bj * 32;
;                     float xo[8]; unpack8(*(const v4u*)(xb + off), xo);
;                     const f32x4 a0 = acc[ai][bj][m][0], a1 = acc[ai][bj][m][1];
;                     const f32x4 y0 = {xo[0] + a0[0], xo[1] + a0[1], xo[2] + a0[2], xo[3] + a0[3]}, y1 = {xo[4] + a1[0], xo[5] + a1[1], xo[6] + a1[2], xo[7] + a1[3]};
;                     v4u w; w.x = pg8::cvt_pk_bf16(y0[0], y0[1]); w.y = pg8::cvt_pk_bf16(y0[2], y0[3]); w.z = pg8::cvt_pk_bf16(y1[0], y1[1]); w.w = pg8::cvt_pk_bf16(y1[2], y1[3]);
;                     *(v4u*)(xb + off) = w;
;                     ss += (y0[0] * y0[0] + y0[1] * y0[1]) + (y0[2] * y0[2] + y0[3] * y0[3]) + (y1[0] * y1[0] + y1[1] * y1[1]) + (y1[2] * y1[2] + y1[3] * y1[3]);
;                 }
;                 ss += __shfl_xor(ss, 16); ss += __shfl_xor(ss, 32);
;                 if (fq == 0) ssq[(size_t)(u.pn * 4 + wc) * T + row] = ss;
;             }
.LBB0_172:
	s_lshl_b32 s2, s17, 8
	s_add_i32 s2, s2, s66
	v_and_or_b32 v0, v219, 15, s2
	s_lshl_b32 s2, s16, 8
	v_lshrrev_b32_e32 v1, 1, v219
	s_or_b32 s2, s2, s67
	v_and_b32_e32 v1, 56, v1
	v_add_u32_e32 v134, s2, v1
	s_lshl_b32 s2, s16, 2
	s_or_b32 s16, s2, s86
	v_ashrrev_i32_e32 v1, 31, v0
	v_readlane_b32 s2, v254, 41
	v_lshlrev_b64 v[132:133], 11, v[0:1]
	v_readlane_b32 s3, v254, 42
	v_ashrrev_i32_e32 v135, 31, v134
	v_cmp_lt_i32_e32 vcc, v225, v220
	v_lshl_add_u64 v[132:133], s[2:3], 0, v[132:133]
	v_lshl_add_u64 v[132:133], v[134:135], 1, v[132:133]
	v_lshlrev_b32_e32 v147, 1, v134
	v_lshl_add_u32 v147, v0, 11, v147
	global_load_dwordx4 v[148:151], v147, s[2:3]
	global_load_dwordx4 v[152:155], v147, s[2:3] offset:64
	v_add_u32_e32 v234, 0x8000, v147
	global_load_dwordx4 v[156:159], v234, s[2:3]
	global_load_dwordx4 v[160:163], v234, s[2:3] offset:64
	v_add_u32_e32 v234, 0x10000, v147
	global_load_dwordx4 v[164:167], v234, s[2:3]
	global_load_dwordx4 v[168:171], v234, s[2:3] offset:64
	v_add_u32_e32 v234, 0x18000, v147
	global_load_dwordx4 v[172:175], v234, s[2:3]
	global_load_dwordx4 v[176:179], v234, s[2:3] offset:64
	v_add_u32_e32 v234, 0x40000, v147
	global_load_dwordx4 v[180:183], v234, s[2:3]
	global_load_dwordx4 v[184:187], v234, s[2:3] offset:64
	v_add_u32_e32 v234, 0x48000, v147
	global_load_dwordx4 v[188:191], v234, s[2:3]
	global_load_dwordx4 v[196:199], v234, s[2:3] offset:64
	v_add_u32_e32 v234, 0x50000, v147
	global_load_dwordx4 v[200:203], v234, s[2:3]
	global_load_dwordx4 v[204:207], v234, s[2:3] offset:64
	v_add_u32_e32 v234, 0x58000, v147
	global_load_dwordx4 v[208:211], v234, s[2:3]
	global_load_dwordx4 v[212:215], v234, s[2:3] offset:64
	s_waitcnt vmcnt(0)
	v_mov_b64_e32 v[140:141], v[148:149]
	v_mov_b64_e32 v[142:143], v[150:151]
	s_ashr_i32 s17, s16, 31
	v_cmp_gt_u32_e64 s[40:41], 16, v219
	s_lshl_b64 s[46:47], s[16:17], 17
	v_lshlrev_b32_e32 v139, 16, v140
	v_and_b32_e32 v140, 0xffff0000, v140
	v_lshlrev_b32_e32 v144, 16, v141
	v_and_b32_e32 v141, 0xffff0000, v141
	v_lshlrev_b32_e32 v145, 16, v142
	v_and_b32_e32 v142, 0xffff0000, v142
	v_lshlrev_b32_e32 v146, 16, v143
	v_and_b32_e32 v143, 0xffff0000, v143
	v_add_f32_e32 v128, v128, v139
	v_add_f32_e32 v129, v129, v140
	v_add_f32_e32 v130, v130, v144
	v_add_f32_e32 v131, v131, v141
	v_add_f32_e32 v139, v124, v145
	v_add_f32_e32 v140, v125, v142
	v_cvt_pk_bf16_f32 v124, v128, v129
	v_cvt_pk_bf16_f32 v125, v130, v131
	v_add_f32_e32 v141, v126, v146
	v_add_f32_e32 v142, v127, v143
	v_cvt_pk_bf16_f32 v126, v139, v140
	v_cvt_pk_bf16_f32 v127, v141, v142
	global_store_dwordx4 v[132:133], v[124:127], off
	s_nop 1
	v_mul_f32_e32 v124, v129, v129
	v_mul_f32_e32 v125, v131, v131
	v_fmac_f32_e32 v124, v128, v128
	v_fmac_f32_e32 v125, v130, v130
	v_add_f32_e32 v124, v124, v125
	v_mul_f32_e32 v125, v140, v140
	v_fmac_f32_e32 v125, v139, v139
	v_add_f32_e32 v124, v125, v124
	v_mul_f32_e32 v125, v142, v142
	v_fmac_f32_e32 v125, v141, v141
	v_add_f32_e32 v128, v125, v124
	v_mov_b64_e32 v[124:125], v[152:153]
	v_mov_b64_e32 v[126:127], v[154:155]
	v_lshlrev_b32_e32 v129, 16, v124
	v_and_b32_e32 v124, 0xffff0000, v124
	v_lshlrev_b32_e32 v130, 16, v125
	v_and_b32_e32 v125, 0xffff0000, v125
	v_lshlrev_b32_e32 v131, 16, v126
	v_and_b32_e32 v126, 0xffff0000, v126
	v_lshlrev_b32_e32 v139, 16, v127
	v_and_b32_e32 v127, 0xffff0000, v127
	v_add_f32_e32 v120, v120, v129
	v_add_f32_e32 v121, v121, v124
	v_add_f32_e32 v122, v122, v130
	v_add_f32_e32 v123, v123, v125
	v_add_f32_e32 v124, v116, v131
	v_add_f32_e32 v125, v117, v126
	v_cvt_pk_bf16_f32 v116, v120, v121
	v_cvt_pk_bf16_f32 v117, v122, v123
	v_add_f32_e32 v126, v118, v139
	v_add_f32_e32 v127, v119, v127
	v_cvt_pk_bf16_f32 v118, v124, v125
	v_cvt_pk_bf16_f32 v119, v126, v127
	global_store_dwordx4 v[132:133], v[116:119], off offset:64
	s_nop 1
	v_mul_f32_e32 v116, v121, v121
	v_mul_f32_e32 v117, v123, v123
	v_fmac_f32_e32 v116, v120, v120
	v_fmac_f32_e32 v117, v122, v122
	v_add_f32_e32 v116, v116, v117
	v_mul_f32_e32 v117, v125, v125
	v_fmac_f32_e32 v117, v124, v124
	v_add_f32_e32 v116, v117, v116
	v_mul_f32_e32 v117, v127, v127
	v_fmac_f32_e32 v117, v126, v126
	v_add_f32_e32 v116, v117, v116
	v_add_f32_e32 v117, v128, v116
	v_cndmask_b32_e32 v116, v219, v225, vcc
	v_lshlrev_b32_e32 v116, 2, v116
	ds_bpermute_b32 v118, v116, v117
	v_cmp_lt_i32_e32 vcc, v226, v220
	s_waitcnt lgkmcnt(0)
	v_add_f32_e32 v118, v117, v118
	v_cndmask_b32_e32 v117, v219, v226, vcc
	v_lshlrev_b32_e32 v117, 2, v117
	ds_bpermute_b32 v119, v117, v118
	s_and_saveexec_b64 s[48:49], s[40:41]
	s_cbranch_execz .LBB0_174
	s_add_u32 s16, s56, s46
	s_addc_u32 s17, s57, s47
	s_waitcnt lgkmcnt(0)
	v_add_f32_e32 v120, v118, v119
	v_lshl_add_u64 v[118:119], v[0:1], 2, s[16:17]
	global_store_dword v[118:119], v120, off
; __device__ __forceinline__ unsigned cvt_pk_bf16(float lo, float hi) { unsigned r; asm volatile("v_cvt_pk_bf16_f32 %0, %1, %2" : "=v"(r) : "v"(lo), "v"(hi)); return r; }
; __device__ __forceinline__ void unpack8(const v4u q, float (&f)[8]) { f[0] = bflo(q.x); f[1] = bfhi(q.x); f[2] = bflo(q.y); f[3] = bfhi(q.y); f[4] = bflo(q.z); f[5] = bfhi(q.z); f[6] = bflo(q.w); f[7] = bfhi(q.w); }
;     __device__ __forceinline__ void operator()(const f32x4 (&acc)[2][2][4][2], const Unit& u, int wr, int wc, int fr, int fq) const {
;         const int row0 = u.pm * 256 + wr * 64 + fr, c = u.pn * 256 + wc * 64 + 8 * fq;
; #pragma unroll
;         for (int ai = 0; ai < 2; ++ai)
; #pragma unroll
;             for (int m = 0; m < 4; ++m) {
;                 const int row = row0 + ai * 128 + m * 16; float ss = 0.f;
; #pragma unroll
;                 for (int bj = 0; bj < 2; ++bj) {
;                     const size_t off = (size_t)row * D + c + bj * 32;
;                     float xo[8]; unpack8(*(const v4u*)(xb + off), xo);
;                     const f32x4 a0 = acc[ai][bj][m][0], a1 = acc[ai][bj][m][1];
;                     const f32x4 y0 = {xo[0] + a0[0], xo[1] + a0[1], xo[2] + a0[2], xo[3] + a0[3]}, y1 = {xo[4] + a1[0], xo[5] + a1[1], xo[6] + a1[2], xo[7] + a1[3]};
;                     v4u w; w.x = pg8::cvt_pk_bf16(y0[0], y0[1]); w.y = pg8::cvt_pk_bf16(y0[2], y0[3]); w.z = pg8::cvt_pk_bf16(y1[0], y1[1]); w.w = pg8::cvt_pk_bf16(y1[2], y1[3]);
;                     *(v4u*)(xb + off) = w;
;                     ss += (y0[0] * y0[0] + y0[1] * y0[1]) + (y0[2] * y0[2] + y0[3] * y0[3]) + (y1[0] * y1[0] + y1[1] * y1[1]) + (y1[2] * y1[2] + y1[3] * y1[3]);
;                 }
;                 ss += __shfl_xor(ss, 16); ss += __shfl_xor(ss, 32);
;                 if (fq == 0) ssq[(size_t)(u.pn * 4 + wc) * T + row] = ss;
;             }
.LBB0_174:
	s_or_b64 exec, exec, s[48:49]
	v_or_b32_e32 v118, 16, v0
	s_waitcnt lgkmcnt(0)
	v_ashrrev_i32_e32 v119, 31, v118
	v_readlane_b32 s2, v254, 41
	v_lshlrev_b64 v[118:119], 11, v[118:119]
	v_readlane_b32 s3, v254, 42
	s_nop 1
	v_lshl_add_u64 v[118:119], s[2:3], 0, v[118:119]
	v_lshl_add_u64 v[122:123], v[134:135], 1, v[118:119]
	v_mov_b64_e32 v[118:119], v[156:157]
	v_mov_b64_e32 v[120:121], v[158:159]
	v_lshlrev_b32_e32 v124, 16, v118
	v_and_b32_e32 v118, 0xffff0000, v118
	v_lshlrev_b32_e32 v125, 16, v119
	v_and_b32_e32 v119, 0xffff0000, v119
	v_lshlrev_b32_e32 v126, 16, v120
	v_and_b32_e32 v120, 0xffff0000, v120
	v_lshlrev_b32_e32 v127, 16, v121
	v_and_b32_e32 v121, 0xffff0000, v121
	v_add_f32_e32 v124, v112, v124
	v_add_f32_e32 v118, v113, v118
	v_add_f32_e32 v125, v114, v125
	v_add_f32_e32 v119, v115, v119
	v_add_f32_e32 v126, v108, v126
	v_add_f32_e32 v120, v109, v120
	v_add_f32_e32 v127, v110, v127
	v_add_f32_e32 v121, v111, v121
	v_cvt_pk_bf16_f32 v108, v124, v118
	v_cvt_pk_bf16_f32 v109, v125, v119
	v_cvt_pk_bf16_f32 v110, v126, v120
	v_cvt_pk_bf16_f32 v111, v127, v121
	v_mov_b64_e32 v[112:113], v[160:161]
	v_mov_b64_e32 v[114:115], v[162:163]
	v_mul_f32_e32 v118, v118, v118
	v_mul_f32_e32 v119, v119, v119
	v_mul_f32_e32 v120, v120, v120
	v_fmac_f32_e32 v118, v124, v124
	v_fmac_f32_e32 v119, v125, v125
	v_mul_f32_e32 v121, v121, v121
	v_fmac_f32_e32 v120, v126, v126
	v_add_f32_e32 v118, v118, v119
	v_fmac_f32_e32 v121, v127, v127
	v_add_f32_e32 v118, v120, v118
	v_add_f32_e32 v118, v121, v118
	global_store_dwordx4 v[122:123], v[108:111], off
	v_lshlrev_b32_e32 v119, 16, v112
	v_and_b32_e32 v112, 0xffff0000, v112
	v_lshlrev_b32_e32 v120, 16, v113
	v_and_b32_e32 v113, 0xffff0000, v113
	v_lshlrev_b32_e32 v121, 16, v114
	v_and_b32_e32 v114, 0xffff0000, v114
	v_add_f32_e32 v105, v105, v112
	v_add_f32_e32 v107, v107, v113
	v_lshlrev_b32_e32 v124, 16, v115
	v_and_b32_e32 v115, 0xffff0000, v115
	v_add_f32_e32 v104, v104, v119
	v_add_f32_e32 v106, v106, v120
	v_add_f32_e32 v112, v100, v121
	v_add_f32_e32 v113, v101, v114
	v_mul_f32_e32 v100, v105, v105
	v_mul_f32_e32 v101, v107, v107
	v_add_f32_e32 v114, v102, v124
	v_add_f32_e32 v115, v103, v115
	v_mul_f32_e32 v102, v113, v113
	v_fmac_f32_e32 v100, v104, v104
	v_fmac_f32_e32 v101, v106, v106
	v_mul_f32_e32 v103, v115, v115
	v_fmac_f32_e32 v102, v112, v112
	v_add_f32_e32 v100, v100, v101
	v_add_f32_e32 v100, v102, v100
	v_fmac_f32_e32 v103, v114, v114
	v_add_f32_e32 v100, v103, v100
	v_add_f32_e32 v100, v118, v100
	ds_bpermute_b32 v101, v116, v100
	v_cvt_pk_bf16_f32 v102, v104, v105
	v_cvt_pk_bf16_f32 v103, v106, v107
	v_cvt_pk_bf16_f32 v104, v112, v113
	v_cvt_pk_bf16_f32 v105, v114, v115
	s_waitcnt lgkmcnt(0)
	v_add_f32_e32 v100, v100, v101
	ds_bpermute_b32 v101, v117, v100
	global_store_dwordx4 v[122:123], v[102:105], off offset:64
	s_and_saveexec_b64 s[48:49], s[40:41]
	s_cbranch_execz .LBB0_176
	s_add_u32 s16, s56, s46
	s_addc_u32 s17, s57, s47
	s_waitcnt lgkmcnt(0)
	v_add_f32_e32 v102, v100, v101
	v_lshl_add_u64 v[100:101], v[0:1], 2, s[16:17]
	global_store_dword v[100:101], v102, off offset:64
.LBB0_176:
	s_or_b64 exec, exec, s[48:49]
	v_or_b32_e32 v100, 32, v0
	s_waitcnt lgkmcnt(0)
	v_ashrrev_i32_e32 v101, 31, v100
	v_readlane_b32 s2, v254, 41
	v_lshlrev_b64 v[100:101], 11, v[100:101]
	v_readlane_b32 s3, v254, 42
	s_nop 1
	v_lshl_add_u64 v[100:101], s[2:3], 0, v[100:101]
	v_lshl_add_u64 v[104:105], v[134:135], 1, v[100:101]
	v_mov_b64_e32 v[100:101], v[164:165]
	v_mov_b64_e32 v[102:103], v[166:167]
	v_lshlrev_b32_e32 v106, 16, v100
	v_and_b32_e32 v100, 0xffff0000, v100
	v_lshlrev_b32_e32 v107, 16, v101
	v_and_b32_e32 v101, 0xffff0000, v101
	v_lshlrev_b32_e32 v108, 16, v102
	v_and_b32_e32 v102, 0xffff0000, v102
	v_lshlrev_b32_e32 v109, 16, v103
	v_and_b32_e32 v103, 0xffff0000, v103
	v_add_f32_e32 v106, v96, v106
	v_add_f32_e32 v100, v97, v100
	v_add_f32_e32 v107, v98, v107
	v_add_f32_e32 v101, v99, v101
	v_add_f32_e32 v108, v92, v108
	v_add_f32_e32 v102, v93, v102
	v_add_f32_e32 v109, v94, v109
	v_add_f32_e32 v103, v95, v103
	v_cvt_pk_bf16_f32 v92, v106, v100
	v_cvt_pk_bf16_f32 v93, v107, v101
	v_cvt_pk_bf16_f32 v94, v108, v102
	v_cvt_pk_bf16_f32 v95, v109, v103
	v_mov_b64_e32 v[96:97], v[168:169]
	v_mov_b64_e32 v[98:99], v[170:171]
	v_mul_f32_e32 v100, v100, v100
	v_mul_f32_e32 v101, v101, v101
	v_mul_f32_e32 v102, v102, v102
	v_fmac_f32_e32 v100, v106, v106
	v_fmac_f32_e32 v101, v107, v107
	v_mul_f32_e32 v103, v103, v103
	v_fmac_f32_e32 v102, v108, v108
	v_add_f32_e32 v100, v100, v101
	v_fmac_f32_e32 v103, v109, v109
	v_add_f32_e32 v100, v102, v100
	v_add_f32_e32 v100, v103, v100
	global_store_dwordx4 v[104:105], v[92:95], off
	v_lshlrev_b32_e32 v101, 16, v96
	v_and_b32_e32 v96, 0xffff0000, v96
	v_lshlrev_b32_e32 v102, 16, v97
	v_and_b32_e32 v97, 0xffff0000, v97
	v_lshlrev_b32_e32 v103, 16, v98
	v_and_b32_e32 v98, 0xffff0000, v98
	v_add_f32_e32 v89, v89, v96
	v_add_f32_e32 v91, v91, v97
	v_lshlrev_b32_e32 v106, 16, v99
	v_and_b32_e32 v99, 0xffff0000, v99
	v_add_f32_e32 v88, v88, v101
	v_add_f32_e32 v90, v90, v102
	v_add_f32_e32 v96, v84, v103
	v_add_f32_e32 v97, v85, v98
	v_mul_f32_e32 v84, v89, v89
	v_mul_f32_e32 v85, v91, v91
	v_add_f32_e32 v98, v86, v106
	v_add_f32_e32 v99, v87, v99
	v_mul_f32_e32 v86, v97, v97
	v_fmac_f32_e32 v84, v88, v88
	v_fmac_f32_e32 v85, v90, v90
	v_mul_f32_e32 v87, v99, v99
	v_fmac_f32_e32 v86, v96, v96
	v_add_f32_e32 v84, v84, v85
	v_add_f32_e32 v84, v86, v84
	v_fmac_f32_e32 v87, v98, v98
	v_add_f32_e32 v84, v87, v84
	v_add_f32_e32 v84, v100, v84
	ds_bpermute_b32 v85, v116, v84
	v_cvt_pk_bf16_f32 v86, v88, v89
	v_cvt_pk_bf16_f32 v87, v90, v91
	v_cvt_pk_bf16_f32 v88, v96, v97
	v_cvt_pk_bf16_f32 v89, v98, v99
	s_waitcnt lgkmcnt(0)
	v_add_f32_e32 v84, v84, v85
	ds_bpermute_b32 v85, v117, v84
	global_store_dwordx4 v[104:105], v[86:89], off offset:64
	s_and_saveexec_b64 s[48:49], s[40:41]
	s_cbranch_execz .LBB0_178
	s_add_u32 s16, s56, s46
	s_addc_u32 s17, s57, s47
	s_waitcnt lgkmcnt(0)
	v_add_f32_e32 v86, v84, v85
	v_lshl_add_u64 v[84:85], v[0:1], 2, s[16:17]
	global_store_dword v[84:85], v86, off offset:128
; __device__ __forceinline__ unsigned cvt_pk_bf16(float lo, float hi) { unsigned r; asm volatile("v_cvt_pk_bf16_f32 %0, %1, %2" : "=v"(r) : "v"(lo), "v"(hi)); return r; }
; __device__ __forceinline__ void unpack8(const v4u q, float (&f)[8]) { f[0] = bflo(q.x); f[1] = bfhi(q.x); f[2] = bflo(q.y); f[3] = bfhi(q.y); f[4] = bflo(q.z); f[5] = bfhi(q.z); f[6] = bflo(q.w); f[7] = bfhi(q.w); }
;     __device__ __forceinline__ void operator()(const f32x4 (&acc)[2][2][4][2], const Unit& u, int wr, int wc, int fr, int fq) const {
;         const int row0 = u.pm * 256 + wr * 64 + fr, c = u.pn * 256 + wc * 64 + 8 * fq;
; #pragma unroll
;         for (int ai = 0; ai < 2; ++ai)
; #pragma unroll
;             for (int m = 0; m < 4; ++m) {
;                 const int row = row0 + ai * 128 + m * 16; float ss = 0.f;
; #pragma unroll
;                 for (int bj = 0; bj < 2; ++bj) {
;                     const size_t off = (size_t)row * D + c + bj * 32;
;                     float xo[8]; unpack8(*(const v4u*)(xb + off), xo);
;                     const f32x4 a0 = acc[ai][bj][m][0], a1 = acc[ai][bj][m][1];
;                     const f32x4 y0 = {xo[0] + a0[0], xo[1] + a0[1], xo[2] + a0[2], xo[3] + a0[3]}, y1 = {xo[4] + a1[0], xo[5] + a1[1], xo[6] + a1[2], xo[7] + a1[3]};
;                     v4u w; w.x = pg8::cvt_pk_bf16(y0[0], y0[1]); w.y = pg8::cvt_pk_bf16(y0[2], y0[3]); w.z = pg8::cvt_pk_bf16(y1[0], y1[1]); w.w = pg8::cvt_pk_bf16(y1[2], y1[3]);
;                     *(v4u*)(xb + off) = w;
;                     ss += (y0[0] * y0[0] + y0[1] * y0[1]) + (y0[2] * y0[2] + y0[3] * y0[3]) + (y1[0] * y1[0] + y1[1] * y1[1]) + (y1[2] * y1[2] + y1[3] * y1[3]);
;                 }
;                 ss += __shfl_xor(ss, 16); ss += __shfl_xor(ss, 32);
;                 if (fq == 0) ssq[(size_t)(u.pn * 4 + wc) * T + row] = ss;
;             }
.LBB0_178:
	s_or_b64 exec, exec, s[48:49]
	v_or_b32_e32 v84, 48, v0
	s_waitcnt lgkmcnt(0)
	v_ashrrev_i32_e32 v85, 31, v84
	v_readlane_b32 s2, v254, 41
	v_lshlrev_b64 v[84:85], 11, v[84:85]
	v_readlane_b32 s3, v254, 42
	s_nop 1
	v_lshl_add_u64 v[84:85], s[2:3], 0, v[84:85]
	v_lshl_add_u64 v[88:89], v[134:135], 1, v[84:85]
	v_mov_b64_e32 v[84:85], v[172:173]
	v_mov_b64_e32 v[86:87], v[174:175]
	v_lshlrev_b32_e32 v90, 16, v84
	v_and_b32_e32 v84, 0xffff0000, v84
	v_lshlrev_b32_e32 v91, 16, v85
	v_and_b32_e32 v85, 0xffff0000, v85
	v_lshlrev_b32_e32 v92, 16, v86
	v_and_b32_e32 v86, 0xffff0000, v86
	v_lshlrev_b32_e32 v93, 16, v87
	v_and_b32_e32 v87, 0xffff0000, v87
	v_add_f32_e32 v90, v80, v90
	v_add_f32_e32 v84, v81, v84
	v_add_f32_e32 v91, v82, v91
	v_add_f32_e32 v85, v83, v85
	v_add_f32_e32 v92, v76, v92
	v_add_f32_e32 v86, v77, v86
	v_add_f32_e32 v93, v78, v93
	v_add_f32_e32 v87, v79, v87
	v_cvt_pk_bf16_f32 v76, v90, v84
	v_cvt_pk_bf16_f32 v77, v91, v85
	v_cvt_pk_bf16_f32 v78, v92, v86
	v_cvt_pk_bf16_f32 v79, v93, v87
	v_mov_b64_e32 v[80:81], v[176:177]
	v_mov_b64_e32 v[82:83], v[178:179]
	v_mul_f32_e32 v84, v84, v84
	v_mul_f32_e32 v85, v85, v85
	v_mul_f32_e32 v86, v86, v86
	v_fmac_f32_e32 v84, v90, v90
	v_fmac_f32_e32 v85, v91, v91
	v_mul_f32_e32 v87, v87, v87
	v_fmac_f32_e32 v86, v92, v92
	v_add_f32_e32 v84, v84, v85
	v_fmac_f32_e32 v87, v93, v93
	v_add_f32_e32 v84, v86, v84
	v_add_f32_e32 v84, v87, v84
	global_store_dwordx4 v[88:89], v[76:79], off
	v_lshlrev_b32_e32 v85, 16, v80
	v_and_b32_e32 v80, 0xffff0000, v80
	v_lshlrev_b32_e32 v86, 16, v81
	v_and_b32_e32 v81, 0xffff0000, v81
	v_lshlrev_b32_e32 v87, 16, v82
	v_and_b32_e32 v82, 0xffff0000, v82
	v_add_f32_e32 v73, v73, v80
	v_add_f32_e32 v75, v75, v81
	v_lshlrev_b32_e32 v90, 16, v83
	v_and_b32_e32 v83, 0xffff0000, v83
	v_add_f32_e32 v72, v72, v85
	v_add_f32_e32 v74, v74, v86
	v_add_f32_e32 v80, v68, v87
	v_add_f32_e32 v81, v69, v82
	v_mul_f32_e32 v68, v73, v73
	v_mul_f32_e32 v69, v75, v75
	v_add_f32_e32 v82, v70, v90
	v_add_f32_e32 v83, v71, v83
	v_mul_f32_e32 v70, v81, v81
	v_fmac_f32_e32 v68, v72, v72
	v_fmac_f32_e32 v69, v74, v74
	v_mul_f32_e32 v71, v83, v83
	v_fmac_f32_e32 v70, v80, v80
	v_add_f32_e32 v68, v68, v69
	v_add_f32_e32 v68, v70, v68
	v_fmac_f32_e32 v71, v82, v82
	v_add_f32_e32 v68, v71, v68
	v_add_f32_e32 v68, v84, v68
	ds_bpermute_b32 v69, v116, v68
	v_cvt_pk_bf16_f32 v70, v72, v73
	v_cvt_pk_bf16_f32 v71, v74, v75
	v_cvt_pk_bf16_f32 v72, v80, v81
	v_cvt_pk_bf16_f32 v73, v82, v83
	s_waitcnt lgkmcnt(0)
	v_add_f32_e32 v68, v68, v69
	ds_bpermute_b32 v69, v117, v68
	global_store_dwordx4 v[88:89], v[70:73], off offset:64
	s_and_saveexec_b64 s[48:49], s[40:41]
	s_cbranch_execz .LBB0_180
	s_add_u32 s16, s56, s46
	s_addc_u32 s17, s57, s47
	s_waitcnt lgkmcnt(0)
	v_add_f32_e32 v70, v68, v69
	v_lshl_add_u64 v[68:69], v[0:1], 2, s[16:17]
	global_store_dword v[68:69], v70, off offset:192
.LBB0_180:
	s_or_b64 exec, exec, s[48:49]
	v_add_co_u32_e32 v72, vcc, 0x40000, v132
	s_mov_b64 s[2:3], 0x40000
	s_nop 0
	v_addc_co_u32_e32 v73, vcc, 0, v133, vcc
	s_waitcnt lgkmcnt(0)
	v_mov_b64_e32 v[68:69], v[180:181]
	v_mov_b64_e32 v[70:71], v[182:183]
	v_lshl_add_u64 v[74:75], v[132:133], 0, s[2:3]
	v_lshlrev_b32_e32 v76, 16, v68
	v_and_b32_e32 v68, 0xffff0000, v68
	v_lshlrev_b32_e32 v77, 16, v69
	v_and_b32_e32 v69, 0xffff0000, v69
	v_lshlrev_b32_e32 v78, 16, v70
	v_and_b32_e32 v70, 0xffff0000, v70
	v_lshlrev_b32_e32 v79, 16, v71
	v_and_b32_e32 v71, 0xffff0000, v71
	v_add_f32_e32 v76, v64, v76
	v_add_f32_e32 v68, v65, v68
	v_add_f32_e32 v77, v66, v77
	v_add_f32_e32 v69, v67, v69
	v_add_f32_e32 v78, v60, v78
	v_add_f32_e32 v70, v61, v70
	v_add_f32_e32 v79, v62, v79
	v_add_f32_e32 v71, v63, v71
	v_cvt_pk_bf16_f32 v60, v76, v68
	v_cvt_pk_bf16_f32 v61, v77, v69
	v_cvt_pk_bf16_f32 v62, v78, v70
	v_cvt_pk_bf16_f32 v63, v79, v71
	v_mov_b64_e32 v[64:65], v[184:185]
	v_mov_b64_e32 v[66:67], v[186:187]
	v_mul_f32_e32 v68, v68, v68
	v_mul_f32_e32 v69, v69, v69
	v_mul_f32_e32 v70, v70, v70
	v_fmac_f32_e32 v68, v76, v76
	v_fmac_f32_e32 v69, v77, v77
	v_mul_f32_e32 v71, v71, v71
	v_fmac_f32_e32 v70, v78, v78
	v_add_f32_e32 v68, v68, v69
	v_fmac_f32_e32 v71, v79, v79
	v_add_f32_e32 v68, v70, v68
	v_add_f32_e32 v68, v71, v68
	global_store_dwordx4 v[72:73], v[60:63], off
	v_lshlrev_b32_e32 v69, 16, v64
	v_and_b32_e32 v64, 0xffff0000, v64
	v_lshlrev_b32_e32 v70, 16, v65
	v_and_b32_e32 v65, 0xffff0000, v65
	v_lshlrev_b32_e32 v71, 16, v66
	v_and_b32_e32 v66, 0xffff0000, v66
	v_add_f32_e32 v57, v57, v64
	v_add_f32_e32 v59, v59, v65
	v_lshlrev_b32_e32 v76, 16, v67
	v_and_b32_e32 v67, 0xffff0000, v67
	v_add_f32_e32 v56, v56, v69
	v_add_f32_e32 v58, v58, v70
	v_add_f32_e32 v64, v52, v71
	v_add_f32_e32 v65, v53, v66
	v_mul_f32_e32 v52, v57, v57
	v_mul_f32_e32 v53, v59, v59
	v_add_f32_e32 v66, v54, v76
	v_add_f32_e32 v67, v55, v67
	v_mul_f32_e32 v54, v65, v65
	v_fmac_f32_e32 v52, v56, v56
	v_fmac_f32_e32 v53, v58, v58
	v_mul_f32_e32 v55, v67, v67
	v_fmac_f32_e32 v54, v64, v64
	v_add_f32_e32 v52, v52, v53
	v_add_f32_e32 v52, v54, v52
	v_fmac_f32_e32 v55, v66, v66
	v_add_f32_e32 v52, v55, v52
	v_add_f32_e32 v52, v68, v52
	ds_bpermute_b32 v53, v116, v52
	v_cvt_pk_bf16_f32 v54, v56, v57
	v_cvt_pk_bf16_f32 v55, v58, v59
	v_cvt_pk_bf16_f32 v56, v64, v65
	v_cvt_pk_bf16_f32 v57, v66, v67
	s_waitcnt lgkmcnt(0)
	v_add_f32_e32 v52, v52, v53
	ds_bpermute_b32 v53, v117, v52
	global_store_dwordx4 v[74:75], v[54:57], off offset:64
	s_and_saveexec_b64 s[48:49], s[40:41]
	s_cbranch_execz .LBB0_182
	s_add_u32 s16, s56, s46
	s_addc_u32 s17, s57, s47
	s_waitcnt lgkmcnt(0)
	v_add_f32_e32 v54, v52, v53
	v_lshl_add_u64 v[52:53], v[0:1], 2, s[16:17]
	global_store_dword v[52:53], v54, off offset:512
; __device__ __forceinline__ unsigned cvt_pk_bf16(float lo, float hi) { unsigned r; asm volatile("v_cvt_pk_bf16_f32 %0, %1, %2" : "=v"(r) : "v"(lo), "v"(hi)); return r; }
; __device__ __forceinline__ void unpack8(const v4u q, float (&f)[8]) { f[0] = bflo(q.x); f[1] = bfhi(q.x); f[2] = bflo(q.y); f[3] = bfhi(q.y); f[4] = bflo(q.z); f[5] = bfhi(q.z); f[6] = bflo(q.w); f[7] = bfhi(q.w); }
;     __device__ __forceinline__ void operator()(const f32x4 (&acc)[2][2][4][2], const Unit& u, int wr, int wc, int fr, int fq) const {
;         const int row0 = u.pm * 256 + wr * 64 + fr, c = u.pn * 256 + wc * 64 + 8 * fq;
; #pragma unroll
;         for (int ai = 0; ai < 2; ++ai)
; #pragma unroll
;             for (int m = 0; m < 4; ++m) {
;                 const int row = row0 + ai * 128 + m * 16; float ss = 0.f;
; #pragma unroll
;                 for (int bj = 0; bj < 2; ++bj) {
;                     const size_t off = (size_t)row * D + c + bj * 32;
;                     float xo[8]; unpack8(*(const v4u*)(xb + off), xo);
;                     const f32x4 a0 = acc[ai][bj][m][0], a1 = acc[ai][bj][m][1];
;                     const f32x4 y0 = {xo[0] + a0[0], xo[1] + a0[1], xo[2] + a0[2], xo[3] + a0[3]}, y1 = {xo[4] + a1[0], xo[5] + a1[1], xo[6] + a1[2], xo[7] + a1[3]};
;                     v4u w; w.x = pg8::cvt_pk_bf16(y0[0], y0[1]); w.y = pg8::cvt_pk_bf16(y0[2], y0[3]); w.z = pg8::cvt_pk_bf16(y1[0], y1[1]); w.w = pg8::cvt_pk_bf16(y1[2], y1[3]);
;                     *(v4u*)(xb + off) = w;
;                     ss += (y0[0] * y0[0] + y0[1] * y0[1]) + (y0[2] * y0[2] + y0[3] * y0[3]) + (y1[0] * y1[0] + y1[1] * y1[1]) + (y1[2] * y1[2] + y1[3] * y1[3]);
;                 }
;                 ss += __shfl_xor(ss, 16); ss += __shfl_xor(ss, 32);
;                 if (fq == 0) ssq[(size_t)(u.pn * 4 + wc) * T + row] = ss;
;             }
.LBB0_182:
	s_or_b64 exec, exec, s[48:49]
	v_add_co_u32_e32 v56, vcc, 0x48000, v132
	s_mov_b64 s[2:3], 0x48000
	s_nop 0
	v_addc_co_u32_e32 v57, vcc, 0, v133, vcc
	s_waitcnt lgkmcnt(0)
	v_mov_b64_e32 v[52:53], v[188:189]
	v_mov_b64_e32 v[54:55], v[190:191]
	v_lshl_add_u64 v[58:59], v[132:133], 0, s[2:3]
	v_lshlrev_b32_e32 v60, 16, v52
	v_and_b32_e32 v52, 0xffff0000, v52
	v_lshlrev_b32_e32 v61, 16, v53
	v_and_b32_e32 v53, 0xffff0000, v53
	v_lshlrev_b32_e32 v62, 16, v54
	v_and_b32_e32 v54, 0xffff0000, v54
	v_lshlrev_b32_e32 v63, 16, v55
	v_and_b32_e32 v55, 0xffff0000, v55
	v_add_f32_e32 v60, v48, v60
	v_add_f32_e32 v52, v49, v52
	v_add_f32_e32 v61, v50, v61
	v_add_f32_e32 v53, v51, v53
	v_add_f32_e32 v62, v44, v62
	v_add_f32_e32 v54, v45, v54
	v_add_f32_e32 v63, v46, v63
	v_add_f32_e32 v55, v47, v55
	v_cvt_pk_bf16_f32 v44, v60, v52
	v_cvt_pk_bf16_f32 v45, v61, v53
	v_cvt_pk_bf16_f32 v46, v62, v54
	v_cvt_pk_bf16_f32 v47, v63, v55
	v_mov_b64_e32 v[48:49], v[196:197]
	v_mov_b64_e32 v[50:51], v[198:199]
	v_mul_f32_e32 v52, v52, v52
	v_mul_f32_e32 v53, v53, v53
	v_mul_f32_e32 v54, v54, v54
	v_fmac_f32_e32 v52, v60, v60
	v_fmac_f32_e32 v53, v61, v61
	v_mul_f32_e32 v55, v55, v55
	v_fmac_f32_e32 v54, v62, v62
	v_add_f32_e32 v52, v52, v53
	v_fmac_f32_e32 v55, v63, v63
	v_add_f32_e32 v52, v54, v52
	v_add_f32_e32 v52, v55, v52
	global_store_dwordx4 v[56:57], v[44:47], off
	v_lshlrev_b32_e32 v53, 16, v48
	v_and_b32_e32 v48, 0xffff0000, v48
	v_lshlrev_b32_e32 v54, 16, v49
	v_and_b32_e32 v49, 0xffff0000, v49
	v_lshlrev_b32_e32 v55, 16, v50
	v_and_b32_e32 v50, 0xffff0000, v50
	v_add_f32_e32 v41, v41, v48
	v_add_f32_e32 v43, v43, v49
	v_lshlrev_b32_e32 v60, 16, v51
	v_and_b32_e32 v51, 0xffff0000, v51
	v_add_f32_e32 v40, v40, v53
	v_add_f32_e32 v42, v42, v54
	v_add_f32_e32 v48, v36, v55
	v_add_f32_e32 v49, v37, v50
	v_mul_f32_e32 v36, v41, v41
	v_mul_f32_e32 v37, v43, v43
	v_add_f32_e32 v50, v38, v60
	v_add_f32_e32 v51, v39, v51
	v_mul_f32_e32 v38, v49, v49
	v_fmac_f32_e32 v36, v40, v40
	v_fmac_f32_e32 v37, v42, v42
	v_mul_f32_e32 v39, v51, v51
	v_fmac_f32_e32 v38, v48, v48
	v_add_f32_e32 v36, v36, v37
	v_add_f32_e32 v36, v38, v36
	v_fmac_f32_e32 v39, v50, v50
	v_add_f32_e32 v36, v39, v36
	v_add_f32_e32 v36, v52, v36
	ds_bpermute_b32 v37, v116, v36
	v_cvt_pk_bf16_f32 v38, v40, v41
	v_cvt_pk_bf16_f32 v39, v42, v43
	v_cvt_pk_bf16_f32 v40, v48, v49
	v_cvt_pk_bf16_f32 v41, v50, v51
	s_waitcnt lgkmcnt(0)
	v_add_f32_e32 v36, v36, v37
	ds_bpermute_b32 v37, v117, v36
	global_store_dwordx4 v[58:59], v[38:41], off offset:64
	s_and_saveexec_b64 s[48:49], s[40:41]
	s_cbranch_execz .LBB0_184
	s_add_u32 s16, s56, s46
	s_addc_u32 s17, s57, s47
	s_waitcnt lgkmcnt(0)
	v_add_f32_e32 v38, v36, v37
	v_lshl_add_u64 v[36:37], v[0:1], 2, s[16:17]
	global_store_dword v[36:37], v38, off offset:576
; __device__ __forceinline__ unsigned cvt_pk_bf16(float lo, float hi) { unsigned r; asm volatile("v_cvt_pk_bf16_f32 %0, %1, %2" : "=v"(r) : "v"(lo), "v"(hi)); return r; }
; __device__ __forceinline__ void unpack8(const v4u q, float (&f)[8]) { f[0] = bflo(q.x); f[1] = bfhi(q.x); f[2] = bflo(q.y); f[3] = bfhi(q.y); f[4] = bflo(q.z); f[5] = bfhi(q.z); f[6] = bflo(q.w); f[7] = bfhi(q.w); }
;     __device__ __forceinline__ void operator()(const f32x4 (&acc)[2][2][4][2], const Unit& u, int wr, int wc, int fr, int fq) const {
;         const int row0 = u.pm * 256 + wr * 64 + fr, c = u.pn * 256 + wc * 64 + 8 * fq;
; #pragma unroll
;         for (int ai = 0; ai < 2; ++ai)
; #pragma unroll
;             for (int m = 0; m < 4; ++m) {
;                 const int row = row0 + ai * 128 + m * 16; float ss = 0.f;
; #pragma unroll
;                 for (int bj = 0; bj < 2; ++bj) {
;                     const size_t off = (size_t)row * D + c + bj * 32;
;                     float xo[8]; unpack8(*(const v4u*)(xb + off), xo);
;                     const f32x4 a0 = acc[ai][bj][m][0], a1 = acc[ai][bj][m][1];
;                     const f32x4 y0 = {xo[0] + a0[0], xo[1] + a0[1], xo[2] + a0[2], xo[3] + a0[3]}, y1 = {xo[4] + a1[0], xo[5] + a1[1], xo[6] + a1[2], xo[7] + a1[3]};
;                     v4u w; w.x = pg8::cvt_pk_bf16(y0[0], y0[1]); w.y = pg8::cvt_pk_bf16(y0[2], y0[3]); w.z = pg8::cvt_pk_bf16(y1[0], y1[1]); w.w = pg8::cvt_pk_bf16(y1[2], y1[3]);
;                     *(v4u*)(xb + off) = w;
;                     ss += (y0[0] * y0[0] + y0[1] * y0[1]) + (y0[2] * y0[2] + y0[3] * y0[3]) + (y1[0] * y1[0] + y1[1] * y1[1]) + (y1[2] * y1[2] + y1[3] * y1[3]);
;                 }
;                 ss += __shfl_xor(ss, 16); ss += __shfl_xor(ss, 32);
;                 if (fq == 0) ssq[(size_t)(u.pn * 4 + wc) * T + row] = ss;
;             }
.LBB0_184:
	s_or_b64 exec, exec, s[48:49]
	v_add_co_u32_e32 v40, vcc, 0x50000, v132
	s_mov_b64 s[2:3], 0x50000
	s_nop 0
	v_addc_co_u32_e32 v41, vcc, 0, v133, vcc
	s_waitcnt lgkmcnt(0)
	v_mov_b64_e32 v[36:37], v[200:201]
	v_mov_b64_e32 v[38:39], v[202:203]
	v_lshl_add_u64 v[42:43], v[132:133], 0, s[2:3]
	v_lshlrev_b32_e32 v44, 16, v36
	v_and_b32_e32 v36, 0xffff0000, v36
	v_lshlrev_b32_e32 v45, 16, v37
	v_and_b32_e32 v37, 0xffff0000, v37
	v_lshlrev_b32_e32 v46, 16, v38
	v_and_b32_e32 v38, 0xffff0000, v38
	v_lshlrev_b32_e32 v47, 16, v39
	v_and_b32_e32 v39, 0xffff0000, v39
	v_add_f32_e32 v44, v32, v44
	v_add_f32_e32 v36, v33, v36
	v_add_f32_e32 v45, v34, v45
	v_add_f32_e32 v37, v35, v37
	v_add_f32_e32 v46, v28, v46
	v_add_f32_e32 v38, v29, v38
	v_add_f32_e32 v47, v30, v47
	v_add_f32_e32 v39, v31, v39
	v_cvt_pk_bf16_f32 v28, v44, v36
	v_cvt_pk_bf16_f32 v29, v45, v37
	v_cvt_pk_bf16_f32 v30, v46, v38
	v_cvt_pk_bf16_f32 v31, v47, v39
	v_mov_b64_e32 v[32:33], v[204:205]
	v_mov_b64_e32 v[34:35], v[206:207]
	v_mul_f32_e32 v36, v36, v36
	v_mul_f32_e32 v37, v37, v37
	v_mul_f32_e32 v38, v38, v38
	v_fmac_f32_e32 v36, v44, v44
	v_fmac_f32_e32 v37, v45, v45
	v_mul_f32_e32 v39, v39, v39
	v_fmac_f32_e32 v38, v46, v46
	v_add_f32_e32 v36, v36, v37
	v_fmac_f32_e32 v39, v47, v47
	v_add_f32_e32 v36, v38, v36
	v_add_f32_e32 v36, v39, v36
	global_store_dwordx4 v[40:41], v[28:31], off
	v_lshlrev_b32_e32 v37, 16, v32
	v_and_b32_e32 v32, 0xffff0000, v32
	v_lshlrev_b32_e32 v38, 16, v33
	v_and_b32_e32 v33, 0xffff0000, v33
	v_lshlrev_b32_e32 v39, 16, v34
	v_and_b32_e32 v34, 0xffff0000, v34
	v_add_f32_e32 v25, v25, v32
	v_add_f32_e32 v27, v27, v33
	v_lshlrev_b32_e32 v44, 16, v35
	v_and_b32_e32 v35, 0xffff0000, v35
	v_add_f32_e32 v24, v24, v37
	v_add_f32_e32 v26, v26, v38
	v_add_f32_e32 v32, v20, v39
	v_add_f32_e32 v33, v21, v34
	v_mul_f32_e32 v20, v25, v25
	v_mul_f32_e32 v21, v27, v27
	v_add_f32_e32 v34, v22, v44
	v_add_f32_e32 v35, v23, v35
	v_mul_f32_e32 v22, v33, v33
	v_fmac_f32_e32 v20, v24, v24
	v_fmac_f32_e32 v21, v26, v26
	v_mul_f32_e32 v23, v35, v35
	v_fmac_f32_e32 v22, v32, v32
	v_add_f32_e32 v20, v20, v21
	v_add_f32_e32 v20, v22, v20
	v_fmac_f32_e32 v23, v34, v34
	v_add_f32_e32 v20, v23, v20
	v_add_f32_e32 v20, v36, v20
	ds_bpermute_b32 v21, v116, v20
	v_cvt_pk_bf16_f32 v22, v24, v25
	v_cvt_pk_bf16_f32 v23, v26, v27
	v_cvt_pk_bf16_f32 v24, v32, v33
	v_cvt_pk_bf16_f32 v25, v34, v35
	s_waitcnt lgkmcnt(0)
	v_add_f32_e32 v20, v20, v21
	ds_bpermute_b32 v21, v117, v20
	global_store_dwordx4 v[42:43], v[22:25], off offset:64
	s_and_saveexec_b64 s[48:49], s[40:41]
	s_cbranch_execz .LBB0_186
	s_add_u32 s16, s56, s46
	s_addc_u32 s17, s57, s47
	s_waitcnt lgkmcnt(0)
	v_add_f32_e32 v22, v20, v21
	v_lshl_add_u64 v[20:21], v[0:1], 2, s[16:17]
	global_store_dword v[20:21], v22, off offset:640
.LBB0_186:
	s_or_b64 exec, exec, s[48:49]
	v_add_co_u32_e32 v26, vcc, 0x58000, v132
	s_mov_b64 s[2:3], 0x58000
	s_nop 0
	v_addc_co_u32_e32 v27, vcc, 0, v133, vcc
	s_waitcnt lgkmcnt(0)
	v_mov_b64_e32 v[20:21], v[208:209]
	v_mov_b64_e32 v[22:23], v[210:211]
	v_lshl_add_u64 v[24:25], v[132:133], 0, s[2:3]
	v_lshlrev_b32_e32 v28, 16, v20
	v_and_b32_e32 v20, 0xffff0000, v20
	v_lshlrev_b32_e32 v29, 16, v21
	v_and_b32_e32 v21, 0xffff0000, v21
	v_lshlrev_b32_e32 v30, 16, v22
	v_and_b32_e32 v22, 0xffff0000, v22
	v_lshlrev_b32_e32 v31, 16, v23
	v_and_b32_e32 v23, 0xffff0000, v23
	v_add_f32_e32 v16, v16, v28
	v_add_f32_e32 v17, v17, v20
	v_add_f32_e32 v18, v18, v29
	v_add_f32_e32 v19, v19, v21
	v_add_f32_e32 v20, v12, v30
	v_add_f32_e32 v21, v13, v22
	v_cvt_pk_bf16_f32 v12, v16, v17
	v_cvt_pk_bf16_f32 v13, v18, v19
	v_add_f32_e32 v22, v14, v31
	v_add_f32_e32 v23, v15, v23
	v_cvt_pk_bf16_f32 v14, v20, v21
	v_cvt_pk_bf16_f32 v15, v22, v23
	global_store_dwordx4 v[26:27], v[12:15], off
	s_nop 1
	v_mul_f32_e32 v12, v17, v17
	v_mul_f32_e32 v13, v19, v19
	v_fmac_f32_e32 v12, v16, v16
	v_fmac_f32_e32 v13, v18, v18
	v_add_f32_e32 v12, v12, v13
	v_mul_f32_e32 v13, v21, v21
	v_fmac_f32_e32 v13, v20, v20
	v_add_f32_e32 v12, v13, v12
	v_mul_f32_e32 v13, v23, v23
	v_fmac_f32_e32 v13, v22, v22
	v_add_f32_e32 v16, v13, v12
	v_mov_b64_e32 v[12:13], v[212:213]
	v_mov_b64_e32 v[14:15], v[214:215]
	v_lshlrev_b32_e32 v17, 16, v12
	v_and_b32_e32 v12, 0xffff0000, v12
	v_lshlrev_b32_e32 v18, 16, v13
	v_and_b32_e32 v13, 0xffff0000, v13
	v_lshlrev_b32_e32 v19, 16, v14
	v_and_b32_e32 v14, 0xffff0000, v14
	v_lshlrev_b32_e32 v20, 16, v15
	v_and_b32_e32 v15, 0xffff0000, v15
	v_add_f32_e32 v8, v8, v17
	v_add_f32_e32 v9, v9, v12
	v_add_f32_e32 v10, v10, v18
	v_add_f32_e32 v11, v11, v13
	v_add_f32_e32 v12, v4, v19
	v_add_f32_e32 v13, v5, v14
	v_cvt_pk_bf16_f32 v4, v8, v9
	v_cvt_pk_bf16_f32 v5, v10, v11
	v_add_f32_e32 v14, v6, v20
	v_add_f32_e32 v15, v7, v15
	v_cvt_pk_bf16_f32 v6, v12, v13
	v_cvt_pk_bf16_f32 v7, v14, v15
	global_store_dwordx4 v[24:25], v[4:7], off offset:64
	s_nop 1
	v_mul_f32_e32 v4, v9, v9
	v_mul_f32_e32 v5, v11, v11
	v_fmac_f32_e32 v4, v8, v8
	v_fmac_f32_e32 v5, v10, v10
	v_add_f32_e32 v4, v4, v5
	v_mul_f32_e32 v5, v13, v13
	v_fmac_f32_e32 v5, v12, v12
	v_add_f32_e32 v4, v5, v4
	v_mul_f32_e32 v5, v15, v15
	v_fmac_f32_e32 v5, v14, v14
	v_add_f32_e32 v4, v5, v4
	v_add_f32_e32 v4, v16, v4
	ds_bpermute_b32 v5, v116, v4
	s_waitcnt lgkmcnt(0)
	v_add_f32_e32 v4, v4, v5
	ds_bpermute_b32 v5, v117, v4
	s_and_saveexec_b64 s[48:49], s[40:41]
	s_cbranch_execz .LBB0_188
	s_add_u32 s16, s56, s46
	s_addc_u32 s17, s57, s47
	s_waitcnt lgkmcnt(0)
	v_add_f32_e32 v4, v4, v5
	v_lshl_add_u64 v[0:1], v[0:1], 2, s[16:17]
	global_store_dword v[0:1], v4, off offset:704

; __device__ __forceinline__ unsigned cvt_pk_bf16(float lo, float hi) { unsigned r; asm volatile("v_cvt_pk_bf16_f32 %0, %1, %2" : "=v"(r) : "v"(lo), "v"(hi)); return r; }
;     __device__ __forceinline__ void operator()(const f32x4 (&acc)[2][2][4][2], const Unit& u, int wr, int wc, int fr, int fq) const {
;         const int row0 = u.pm * 256 + wr * 64 + fr, c = u.pn * 128 + wc * 32 + 8 * fq;
; #pragma unroll
;         for (int ai = 0; ai < 2; ++ai)
; #pragma unroll
;             for (int m = 0; m < 4; ++m) {
;                 const int row = row0 + ai * 128 + m * 16;
;                 const v4u ga = *(const v4u*)(gates + (size_t)row * NGATE + c), gb = *(const v4u*)(gates + (size_t)row * NGATE + D + c);
;                 const f32x4 a0 = acc[ai][0][m][0], a1 = acc[ai][0][m][1], b0 = acc[ai][1][m][0], b1 = acc[ai][1][m][1];
;                 v4u w;
;                 w.x = pg8::cvt_pk_bf16(bflo(ga.x) * a0[0] + bflo(gb.x) * b0[0], bfhi(ga.x) * a0[1] + bfhi(gb.x) * b0[1]);
;                 w.y = pg8::cvt_pk_bf16(bflo(ga.y) * a0[2] + bflo(gb.y) * b0[2], bfhi(ga.y) * a0[3] + bfhi(gb.y) * b0[3]);
;                 w.z = pg8::cvt_pk_bf16(bflo(ga.z) * a1[0] + bflo(gb.z) * b1[0], bfhi(ga.z) * a1[1] + bfhi(gb.z) * b1[1]);
;                 w.w = pg8::cvt_pk_bf16(bflo(ga.w) * a1[2] + bflo(gb.w) * b1[2], bfhi(ga.w) * a1[3] + bfhi(gb.w) * b1[3]);
;                 *(v4u*)(merged + (size_t)row * D + c) = w;
;             }
.LBB0_212:
	s_lshl_b32 s2, s2, 8
	s_add_i32 s2, s2, s65
	v_and_or_b32 v116, v219, 15, s2
	s_lshl_b32 s2, s92, 7
	v_lshrrev_b32_e32 v0, 1, v219
	s_or_b32 s2, s2, s93
	v_and_b32_e32 v0, 56, v0
	v_add_u32_e32 v0, s2, v0
	v_ashrrev_i32_e32 v117, 31, v116
	v_ashrrev_i32_e32 v1, 31, v0
	v_lshlrev_b64 v[118:119], 12, v[116:117]
	v_lshl_add_u64 v[118:119], s[98:99], 0, v[118:119]
	v_lshlrev_b64 v[0:1], 1, v[0:1]
	v_lshl_add_u64 v[122:123], v[118:119], 0, v[0:1]
	v_lshl_add_u32 v130, v116, 12, v0
	global_load_dwordx4 v[132:135], v130, s[98:99]
	global_load_dwordx4 v[136:139], v130, s[98:99] offset:2048
	v_add_u32_e32 v131, 0x10000, v130
	global_load_dwordx4 v[140:143], v131, s[98:99]
	global_load_dwordx4 v[196:199], v131, s[98:99] offset:2048
	v_add_u32_e32 v131, 0x20000, v130
	global_load_dwordx4 v[200:203], v131, s[98:99]
	global_load_dwordx4 v[208:211], v131, s[98:99] offset:2048
	v_add_u32_e32 v131, 0x30000, v130
	global_load_dwordx4 v[212:215], v131, s[98:99]
	global_load_dwordx4 v[236:239], v131, s[98:99] offset:2048
	v_add_u32_e32 v131, 0x80000, v130
	global_load_dwordx4 v[240:243], v131, s[98:99]
	global_load_dwordx4 v[244:247], v131, s[98:99] offset:2048
	s_waitcnt vmcnt(0)
	v_mov_b64_e32 v[118:119], v[132:133]
	v_mov_b64_e32 v[120:121], v[134:135]
	s_nop 0
	v_mov_b64_e32 v[122:123], v[136:137]
	v_mov_b64_e32 v[124:125], v[138:139]
	v_mov_b32_e32 v128, v188
	v_mov_b32_e32 v129, v180
	v_mov_b32_e32 v180, v189
	s_mov_b64 s[46:47], -1
	s_andn2_b64 vcc, exec, s[38:39]
	v_lshlrev_b32_e32 v126, 16, v118
	v_lshlrev_b32_e32 v127, 16, v122
	v_pk_mul_f32 v[126:127], v[128:129], v[126:127]
	v_mov_b32_e32 v129, v182
	v_add_f32_e32 v128, v126, v127
	v_and_b32_e32 v127, 0xffff0000, v122
	v_and_b32_e32 v126, 0xffff0000, v118
	v_pk_mul_f32 v[126:127], v[180:181], v[126:127]
	v_and_b32_e32 v122, 0xffff0000, v119
	v_add_f32_e32 v118, v126, v127
	v_cvt_pk_bf16_f32 v118, v128, v118
	v_lshlrev_b32_e32 v127, 16, v123
	v_lshlrev_b32_e32 v126, 16, v119
	v_mov_b32_e32 v128, v190
	v_and_b32_e32 v123, 0xffff0000, v123
	v_mov_b32_e32 v182, v191
	v_pk_mul_f32 v[126:127], v[128:129], v[126:127]
	v_pk_mul_f32 v[122:123], v[182:183], v[122:123]
	v_add_f32_e32 v126, v126, v127
	v_add_f32_e32 v119, v122, v123
	v_cvt_pk_bf16_f32 v119, v126, v119
	v_lshlrev_b32_e32 v123, 16, v124
	v_lshlrev_b32_e32 v122, 16, v120
	v_mov_b32_e32 v126, v184
	v_mov_b32_e32 v127, v112
	v_pk_mul_f32 v[122:123], v[126:127], v[122:123]
	v_mov_b32_e32 v112, v185
	v_add_f32_e32 v126, v122, v123
	v_and_b32_e32 v123, 0xffff0000, v124
	v_and_b32_e32 v122, 0xffff0000, v120
	v_pk_mul_f32 v[112:113], v[112:113], v[122:123]
	v_mov_b32_e32 v122, v186
	v_add_f32_e32 v112, v112, v113
	v_cvt_pk_bf16_f32 v120, v126, v112
	v_lshlrev_b32_e32 v113, 16, v125
	v_lshlrev_b32_e32 v112, 16, v121
	v_mov_b32_e32 v123, v114
	v_pk_mul_f32 v[112:113], v[122:123], v[112:113]
	v_mov_b32_e32 v114, v187
	v_add_f32_e32 v122, v112, v113
	v_and_b32_e32 v113, 0xffff0000, v125
	v_and_b32_e32 v112, 0xffff0000, v121
	v_pk_mul_f32 v[112:113], v[114:115], v[112:113]
	v_mov_b32_e32 v126, v176
	v_add_f32_e32 v112, v112, v113
	v_cvt_pk_bf16_f32 v121, v122, v112
	v_lshlrev_b64 v[112:113], 11, v[116:117]
	v_lshl_add_u64 v[112:113], s[62:63], 0, v[112:113]
	v_lshl_add_u64 v[112:113], v[112:113], 0, v[0:1]
	global_store_dwordx4 v[112:113], v[118:121], off
	v_mov_b32_e32 v127, v104
	v_mov_b32_e32 v104, v177
	v_or_b32_e32 v118, 16, v116
	v_ashrrev_i32_e32 v119, 31, v118
	v_lshlrev_b64 v[112:113], 12, v[118:119]
	v_lshl_add_u64 v[112:113], s[98:99], 0, v[112:113]
	v_lshl_add_u64 v[120:121], v[112:113], 0, v[0:1]
	v_mov_b64_e32 v[112:113], v[140:141]
	v_mov_b64_e32 v[114:115], v[142:143]
	s_nop 0
	v_mov_b64_e32 v[120:121], v[196:197]
	v_mov_b64_e32 v[122:123], v[198:199]
	v_lshlrev_b32_e32 v124, 16, v112
	v_lshlrev_b32_e32 v125, 16, v120
	v_pk_mul_f32 v[124:125], v[126:127], v[124:125]
	v_mov_b32_e32 v126, v178
	v_add_f32_e32 v117, v124, v125
	v_and_b32_e32 v125, 0xffff0000, v120
	v_and_b32_e32 v124, 0xffff0000, v112
	v_pk_mul_f32 v[104:105], v[104:105], v[124:125]
	v_lshlrev_b32_e32 v125, 16, v121
	v_lshlrev_b32_e32 v124, 16, v113
	v_mov_b32_e32 v127, v106
	v_and_b32_e32 v121, 0xffff0000, v121
	v_and_b32_e32 v120, 0xffff0000, v113
	v_mov_b32_e32 v106, v179
	v_pk_mul_f32 v[124:125], v[126:127], v[124:125]
	v_pk_mul_f32 v[106:107], v[106:107], v[120:121]
	v_add_f32_e32 v104, v104, v105
	v_add_f32_e32 v105, v124, v125
	v_add_f32_e32 v106, v106, v107
	v_cvt_pk_bf16_f32 v104, v117, v104
	v_cvt_pk_bf16_f32 v105, v105, v106
	v_lshlrev_b32_e32 v107, 16, v122
	v_lshlrev_b32_e32 v106, 16, v114
	v_mov_b32_e32 v112, v108
	v_mov_b32_e32 v113, v96
	v_pk_mul_f32 v[106:107], v[112:113], v[106:107]
	v_mov_b32_e32 v96, v109
	v_add_f32_e32 v108, v106, v107
	v_and_b32_e32 v107, 0xffff0000, v122
	v_and_b32_e32 v106, 0xffff0000, v114
	v_pk_mul_f32 v[96:97], v[96:97], v[106:107]
	v_mov_b32_e32 v109, v98
	v_add_f32_e32 v96, v96, v97
	v_cvt_pk_bf16_f32 v106, v108, v96
	v_lshlrev_b32_e32 v97, 16, v123
	v_lshlrev_b32_e32 v96, 16, v115
	v_mov_b32_e32 v108, v110
	v_pk_mul_f32 v[96:97], v[108:109], v[96:97]
	v_mov_b32_e32 v98, v111
	v_add_f32_e32 v107, v96, v97
	v_and_b32_e32 v97, 0xffff0000, v123
	v_and_b32_e32 v96, 0xffff0000, v115
	v_pk_mul_f32 v[96:97], v[98:99], v[96:97]
	v_mov_b32_e32 v112, v100
	v_add_f32_e32 v96, v96, v97
	v_cvt_pk_bf16_f32 v107, v107, v96
	v_lshlrev_b64 v[96:97], 11, v[118:119]
	v_lshl_add_u64 v[96:97], s[62:63], 0, v[96:97]
	v_lshl_add_u64 v[96:97], v[96:97], 0, v[0:1]
	global_store_dwordx4 v[96:97], v[104:107], off
	v_mov_b32_e32 v113, v88
	v_mov_b32_e32 v88, v101
	v_or_b32_e32 v104, 32, v116
	v_ashrrev_i32_e32 v105, 31, v104
; __device__ __forceinline__ unsigned cvt_pk_bf16(float lo, float hi) { unsigned r; asm volatile("v_cvt_pk_bf16_f32 %0, %1, %2" : "=v"(r) : "v"(lo), "v"(hi)); return r; }
;     __device__ __forceinline__ void operator()(const f32x4 (&acc)[2][2][4][2], const Unit& u, int wr, int wc, int fr, int fq) const {
;         const int row0 = u.pm * 256 + wr * 64 + fr, c = u.pn * 128 + wc * 32 + 8 * fq;
; #pragma unroll
;         for (int ai = 0; ai < 2; ++ai)
; #pragma unroll
;             for (int m = 0; m < 4; ++m) {
;                 const int row = row0 + ai * 128 + m * 16;
;                 const v4u ga = *(const v4u*)(gates + (size_t)row * NGATE + c), gb = *(const v4u*)(gates + (size_t)row * NGATE + D + c);
;                 const f32x4 a0 = acc[ai][0][m][0], a1 = acc[ai][0][m][1], b0 = acc[ai][1][m][0], b1 = acc[ai][1][m][1];
;                 v4u w;
;                 w.x = pg8::cvt_pk_bf16(bflo(ga.x) * a0[0] + bflo(gb.x) * b0[0], bfhi(ga.x) * a0[1] + bfhi(gb.x) * b0[1]);
;                 w.y = pg8::cvt_pk_bf16(bflo(ga.y) * a0[2] + bflo(gb.y) * b0[2], bfhi(ga.y) * a0[3] + bfhi(gb.y) * b0[3]);
;                 w.z = pg8::cvt_pk_bf16(bflo(ga.z) * a1[0] + bflo(gb.z) * b1[0], bfhi(ga.z) * a1[1] + bfhi(gb.z) * b1[1]);
;                 w.w = pg8::cvt_pk_bf16(bflo(ga.w) * a1[2] + bflo(gb.w) * b1[2], bfhi(ga.w) * a1[3] + bfhi(gb.w) * b1[3]);
;                 *(v4u*)(merged + (size_t)row * D + c) = w;
;             }
	v_lshlrev_b64 v[96:97], 12, v[104:105]
	v_lshl_add_u64 v[96:97], s[98:99], 0, v[96:97]
	v_lshl_add_u64 v[106:107], v[96:97], 0, v[0:1]
	v_mov_b64_e32 v[96:97], v[200:201]
	v_mov_b64_e32 v[98:99], v[202:203]
	s_nop 0
	v_mov_b64_e32 v[106:107], v[208:209]
	v_mov_b64_e32 v[108:109], v[210:211]
	v_add_u32_e32 v131, 0x90000, v130
	global_load_dwordx4 v[132:135], v131, s[98:99]
	global_load_dwordx4 v[136:139], v131, s[98:99] offset:2048
	v_add_u32_e32 v131, 0xa0000, v130
	global_load_dwordx4 v[140:143], v131, s[98:99]
	global_load_dwordx4 v[196:199], v131, s[98:99] offset:2048
	v_add_u32_e32 v131, 0xb0000, v130
	global_load_dwordx4 v[200:203], v131, s[98:99]
	global_load_dwordx4 v[208:211], v131, s[98:99] offset:2048
	v_lshlrev_b32_e32 v110, 16, v96
	v_lshlrev_b32_e32 v111, 16, v106
	v_pk_mul_f32 v[110:111], v[112:113], v[110:111]
	v_lshlrev_b32_e32 v101, 16, v107
	v_add_f32_e32 v100, v110, v111
	v_and_b32_e32 v111, 0xffff0000, v106
	v_and_b32_e32 v110, 0xffff0000, v96
	v_pk_mul_f32 v[88:89], v[88:89], v[110:111]
	v_mov_b32_e32 v110, v102
	v_add_f32_e32 v88, v88, v89
	v_cvt_pk_bf16_f32 v88, v100, v88
	v_lshlrev_b32_e32 v100, 16, v97
	v_mov_b32_e32 v111, v90
	v_pk_mul_f32 v[100:101], v[110:111], v[100:101]
	v_mov_b32_e32 v90, v103
	v_add_f32_e32 v89, v100, v101
	v_and_b32_e32 v101, 0xffff0000, v107
	v_and_b32_e32 v100, 0xffff0000, v97
	v_pk_mul_f32 v[90:91], v[90:91], v[100:101]
	v_mov_b32_e32 v96, v92
	v_add_f32_e32 v90, v90, v91
	v_cvt_pk_bf16_f32 v89, v89, v90
	v_lshlrev_b32_e32 v91, 16, v108
	v_lshlrev_b32_e32 v90, 16, v98
	v_mov_b32_e32 v97, v80
	v_pk_mul_f32 v[90:91], v[96:97], v[90:91]
	v_mov_b32_e32 v80, v93
	v_add_f32_e32 v92, v90, v91
	v_and_b32_e32 v91, 0xffff0000, v108
	v_and_b32_e32 v90, 0xffff0000, v98
	v_pk_mul_f32 v[80:81], v[80:81], v[90:91]
	v_mov_b32_e32 v93, v82
	v_add_f32_e32 v80, v80, v81
	v_cvt_pk_bf16_f32 v90, v92, v80
	v_lshlrev_b32_e32 v81, 16, v109
	v_lshlrev_b32_e32 v80, 16, v99
	v_mov_b32_e32 v92, v94
	v_pk_mul_f32 v[80:81], v[92:93], v[80:81]
	v_mov_b32_e32 v82, v95
	v_add_f32_e32 v91, v80, v81
	v_and_b32_e32 v81, 0xffff0000, v109
	v_and_b32_e32 v80, 0xffff0000, v99
	v_pk_mul_f32 v[80:81], v[82:83], v[80:81]
	v_mov_b32_e32 v96, v84
	v_add_f32_e32 v80, v80, v81
	v_cvt_pk_bf16_f32 v91, v91, v80
	v_lshlrev_b64 v[80:81], 11, v[104:105]
	v_lshl_add_u64 v[80:81], s[62:63], 0, v[80:81]
	v_lshl_add_u64 v[80:81], v[80:81], 0, v[0:1]
	global_store_dwordx4 v[80:81], v[88:91], off
	v_mov_b32_e32 v97, v72
	v_mov_b32_e32 v72, v85
	v_or_b32_e32 v88, 48, v116
	v_ashrrev_i32_e32 v89, 31, v88
	v_lshlrev_b64 v[80:81], 12, v[88:89]
	v_lshl_add_u64 v[80:81], s[98:99], 0, v[80:81]
	v_lshl_add_u64 v[90:91], v[80:81], 0, v[0:1]
	v_mov_b64_e32 v[80:81], v[212:213]
	v_mov_b64_e32 v[82:83], v[214:215]
	s_nop 0
	v_mov_b64_e32 v[90:91], v[236:237]
	v_mov_b64_e32 v[92:93], v[238:239]
	v_lshlrev_b32_e32 v94, 16, v80
	v_lshlrev_b32_e32 v95, 16, v90
	v_pk_mul_f32 v[94:95], v[96:97], v[94:95]
	v_lshlrev_b32_e32 v85, 16, v91
	v_add_f32_e32 v84, v94, v95
	v_and_b32_e32 v95, 0xffff0000, v90
	v_and_b32_e32 v94, 0xffff0000, v80
	v_pk_mul_f32 v[72:73], v[72:73], v[94:95]
	v_mov_b32_e32 v94, v86
	v_add_f32_e32 v72, v72, v73
	v_cvt_pk_bf16_f32 v72, v84, v72
	v_lshlrev_b32_e32 v84, 16, v81
	v_mov_b32_e32 v95, v74
	v_pk_mul_f32 v[84:85], v[94:95], v[84:85]
	v_mov_b32_e32 v74, v87
	v_add_f32_e32 v73, v84, v85
	v_and_b32_e32 v85, 0xffff0000, v91
	v_and_b32_e32 v84, 0xffff0000, v81
	v_pk_mul_f32 v[74:75], v[74:75], v[84:85]
	v_mov_b32_e32 v80, v76
	v_add_f32_e32 v74, v74, v75
	v_cvt_pk_bf16_f32 v73, v73, v74
	v_lshlrev_b32_e32 v75, 16, v92
	v_lshlrev_b32_e32 v74, 16, v82
	v_mov_b32_e32 v81, v64
	v_pk_mul_f32 v[74:75], v[80:81], v[74:75]
	v_mov_b32_e32 v64, v77
	v_add_f32_e32 v76, v74, v75
	v_and_b32_e32 v75, 0xffff0000, v92
	v_and_b32_e32 v74, 0xffff0000, v82
	v_pk_mul_f32 v[64:65], v[64:65], v[74:75]
	v_mov_b32_e32 v77, v66
	v_add_f32_e32 v64, v64, v65
	v_cvt_pk_bf16_f32 v74, v76, v64
	v_lshlrev_b32_e32 v65, 16, v93
	v_lshlrev_b32_e32 v64, 16, v83
	v_mov_b32_e32 v76, v78
	v_pk_mul_f32 v[64:65], v[76:77], v[64:65]
	v_mov_b32_e32 v66, v79
	v_add_f32_e32 v75, v64, v65
	v_and_b32_e32 v65, 0xffff0000, v93
	v_and_b32_e32 v64, 0xffff0000, v83
	v_pk_mul_f32 v[64:65], v[66:67], v[64:65]
	v_mov_b32_e32 v80, v68
	v_add_f32_e32 v64, v64, v65
	v_cvt_pk_bf16_f32 v75, v75, v64
	v_lshlrev_b64 v[64:65], 11, v[88:89]
	v_lshl_add_u64 v[64:65], s[62:63], 0, v[64:65]
	v_lshl_add_u64 v[64:65], v[64:65], 0, v[0:1]
	global_store_dwordx4 v[64:65], v[72:75], off
	v_mov_b32_e32 v81, v52
	v_mov_b32_e32 v52, v69
	v_add_u32_e32 v72, 0x80, v116
	v_ashrrev_i32_e32 v73, 31, v72
	v_lshlrev_b64 v[64:65], 12, v[72:73]
	v_lshl_add_u64 v[64:65], s[98:99], 0, v[64:65]
	v_lshl_add_u64 v[74:75], v[64:65], 0, v[0:1]
	v_mov_b64_e32 v[64:65], v[240:241]
	v_mov_b64_e32 v[66:67], v[242:243]
	s_nop 0
	v_mov_b64_e32 v[74:75], v[244:245]
	v_mov_b64_e32 v[76:77], v[246:247]
	v_lshlrev_b32_e32 v78, 16, v64
	v_lshlrev_b32_e32 v79, 16, v74
	v_pk_mul_f32 v[78:79], v[80:81], v[78:79]
	v_lshlrev_b32_e32 v69, 16, v75
	v_add_f32_e32 v68, v78, v79
	v_and_b32_e32 v79, 0xffff0000, v74
	v_and_b32_e32 v78, 0xffff0000, v64
	v_pk_mul_f32 v[52:53], v[52:53], v[78:79]
	v_mov_b32_e32 v78, v70
	v_add_f32_e32 v52, v52, v53
	v_cvt_pk_bf16_f32 v52, v68, v52
	v_lshlrev_b32_e32 v68, 16, v65
	v_mov_b32_e32 v79, v54
	v_pk_mul_f32 v[68:69], v[78:79], v[68:69]
	v_mov_b32_e32 v54, v71
	v_add_f32_e32 v53, v68, v69
	v_and_b32_e32 v69, 0xffff0000, v75
	v_and_b32_e32 v68, 0xffff0000, v65
	v_pk_mul_f32 v[54:55], v[54:55], v[68:69]
	v_mov_b32_e32 v64, v60
	v_add_f32_e32 v54, v54, v55
	v_cvt_pk_bf16_f32 v53, v53, v54
	v_lshlrev_b32_e32 v55, 16, v76
	v_lshlrev_b32_e32 v54, 16, v66
	v_mov_b32_e32 v65, v44
	v_pk_mul_f32 v[54:55], v[64:65], v[54:55]
	v_mov_b32_e32 v44, v61
	v_add_f32_e32 v60, v54, v55
	v_and_b32_e32 v55, 0xffff0000, v76
	v_and_b32_e32 v54, 0xffff0000, v66
	v_pk_mul_f32 v[44:45], v[44:45], v[54:55]
	v_mov_b32_e32 v61, v46
	v_add_f32_e32 v44, v44, v45
	v_cvt_pk_bf16_f32 v54, v60, v44
	v_lshlrev_b32_e32 v45, 16, v77
	v_lshlrev_b32_e32 v44, 16, v67
	v_mov_b32_e32 v60, v62
	v_pk_mul_f32 v[44:45], v[60:61], v[44:45]
	v_mov_b32_e32 v46, v63
	v_add_f32_e32 v55, v44, v45
	v_and_b32_e32 v45, 0xffff0000, v77
	v_and_b32_e32 v44, 0xffff0000, v67
	v_pk_mul_f32 v[44:45], v[46:47], v[44:45]
	v_mov_b32_e32 v64, v56
	v_add_f32_e32 v44, v44, v45
	v_cvt_pk_bf16_f32 v55, v55, v44
	v_lshlrev_b64 v[44:45], 11, v[72:73]
	v_lshl_add_u64 v[44:45], s[62:63], 0, v[44:45]
	v_lshl_add_u64 v[44:45], v[44:45], 0, v[0:1]
	global_store_dwordx4 v[44:45], v[52:55], off
	v_mov_b32_e32 v65, v36
	v_mov_b32_e32 v36, v57
	v_add_u32_e32 v52, 0x90, v116
	v_ashrrev_i32_e32 v53, 31, v52
	v_lshlrev_b64 v[44:45], 12, v[52:53]
	v_lshl_add_u64 v[44:45], s[98:99], 0, v[44:45]
	v_lshl_add_u64 v[54:55], v[44:45], 0, v[0:1]
	s_waitcnt vmcnt(3)
; __device__ __forceinline__ unsigned cvt_pk_bf16(float lo, float hi) { unsigned r; asm volatile("v_cvt_pk_bf16_f32 %0, %1, %2" : "=v"(r) : "v"(lo), "v"(hi)); return r; }
; #define PG8_BAR __builtin_amdgcn_s_barrier()
; template <class Epi, class Sched, bool ALIGN_EPI = false, bool SP2 = false, bool HALFK = false>
; __device__ __forceinline__ void gemm_phase(PG8_LAS unsigned char* lds, const Gemm g, const Sched& S, const Epi& E, const int tid) {
;     ...
;         if (!has_next) break;
; #pragma unroll
;         for (int a = 0; a < 2; ++a)
; #pragma unroll
;             for (int b = 0; b < 2; ++b)
; #pragma unroll
;                 for (int m = 0; m < 4; ++m)
; #pragma unroll
;                     for (int n = 0; n < 2; ++n) acc[a][b][m][n] = (f32x4){0.f, 0.f, 0.f, 0.f};
;         cur = nxt; cA = nA; cB = nB; ++ui;
;         if constexpr (ALIGN_EPI) { if (wr == 1) PG8_BAR; }
;     __device__ __forceinline__ void operator()(const f32x4 (&acc)[2][2][4][2], const Unit& u, int wr, int wc, int fr, int fq) const {
;         const int row0 = u.pm * 256 + wr * 64 + fr, c = u.pn * 128 + wc * 32 + 8 * fq;
; #pragma unroll
;         for (int ai = 0; ai < 2; ++ai)
; #pragma unroll
;             for (int m = 0; m < 4; ++m) {
;                 const int row = row0 + ai * 128 + m * 16;
;                 const v4u ga = *(const v4u*)(gates + (size_t)row * NGATE + c), gb = *(const v4u*)(gates + (size_t)row * NGATE + D + c);
;                 const f32x4 a0 = acc[ai][0][m][0], a1 = acc[ai][0][m][1], b0 = acc[ai][1][m][0], b1 = acc[ai][1][m][1];
;                 v4u w;
;                 w.x = pg8::cvt_pk_bf16(bflo(ga.x) * a0[0] + bflo(gb.x) * b0[0], bfhi(ga.x) * a0[1] + bfhi(gb.x) * b0[1]);
;                 w.y = pg8::cvt_pk_bf16(bflo(ga.y) * a0[2] + bflo(gb.y) * b0[2], bfhi(ga.y) * a0[3] + bfhi(gb.y) * b0[3]);
;                 w.z = pg8::cvt_pk_bf16(bflo(ga.z) * a1[0] + bflo(gb.z) * b1[0], bfhi(ga.z) * a1[1] + bfhi(gb.z) * b1[1]);
;                 w.w = pg8::cvt_pk_bf16(bflo(ga.w) * a1[2] + bflo(gb.w) * b1[2], bfhi(ga.w) * a1[3] + bfhi(gb.w) * b1[3]);
;                 *(v4u*)(merged + (size_t)row * D + c) = w;
;             }
	v_mov_b64_e32 v[44:45], v[132:133]
	v_mov_b64_e32 v[46:47], v[134:135]
	v_mov_b64_e32 v[60:61], v[136:137]
	v_mov_b64_e32 v[62:63], v[138:139]
	v_mov_b32_e32 v57, v38
	v_mov_b32_e32 v38, v59
	v_lshlrev_b32_e32 v54, 16, v44
	v_lshlrev_b32_e32 v55, 16, v60
	v_pk_mul_f32 v[54:55], v[64:65], v[54:55]
	s_nop 0
	v_add_f32_e32 v56, v54, v55
	v_and_b32_e32 v55, 0xffff0000, v60
	v_and_b32_e32 v54, 0xffff0000, v44
	v_pk_mul_f32 v[36:37], v[36:37], v[54:55]
	v_lshlrev_b32_e32 v55, 16, v61
	v_add_f32_e32 v36, v36, v37
	v_cvt_pk_bf16_f32 v36, v56, v36
	v_lshlrev_b32_e32 v54, 16, v45
	v_mov_b32_e32 v56, v58
	v_pk_mul_f32 v[54:55], v[56:57], v[54:55]
	v_mov_b32_e32 v44, v48
	v_add_f32_e32 v37, v54, v55
	v_and_b32_e32 v55, 0xffff0000, v61
	v_and_b32_e32 v54, 0xffff0000, v45
	v_pk_mul_f32 v[38:39], v[38:39], v[54:55]
	v_mov_b32_e32 v45, v28
	v_add_f32_e32 v38, v38, v39
	v_cvt_pk_bf16_f32 v37, v37, v38
	v_lshlrev_b32_e32 v39, 16, v62
	v_lshlrev_b32_e32 v38, 16, v46
	v_pk_mul_f32 v[38:39], v[44:45], v[38:39]
	v_mov_b32_e32 v28, v49
	v_add_f32_e32 v44, v38, v39
	v_and_b32_e32 v39, 0xffff0000, v62
	v_and_b32_e32 v38, 0xffff0000, v46
	v_pk_mul_f32 v[28:29], v[28:29], v[38:39]
	v_mov_b32_e32 v45, v30
	v_add_f32_e32 v28, v28, v29
	v_cvt_pk_bf16_f32 v38, v44, v28
	v_lshlrev_b32_e32 v29, 16, v63
	v_lshlrev_b32_e32 v28, 16, v47
	v_mov_b32_e32 v44, v50
	v_pk_mul_f32 v[28:29], v[44:45], v[28:29]
	v_mov_b32_e32 v30, v51
	v_add_f32_e32 v39, v28, v29
	v_and_b32_e32 v29, 0xffff0000, v63
	v_and_b32_e32 v28, 0xffff0000, v47
	v_pk_mul_f32 v[28:29], v[30:31], v[28:29]
	v_mov_b32_e32 v48, v40
	v_add_f32_e32 v28, v28, v29
	v_cvt_pk_bf16_f32 v39, v39, v28
	v_lshlrev_b64 v[28:29], 11, v[52:53]
	v_lshl_add_u64 v[28:29], s[62:63], 0, v[28:29]
	v_lshl_add_u64 v[28:29], v[28:29], 0, v[0:1]
	global_store_dwordx4 v[28:29], v[36:39], off
	v_mov_b32_e32 v49, v20
	v_mov_b32_e32 v20, v41
	v_add_u32_e32 v36, 0xa0, v116
	v_ashrrev_i32_e32 v37, 31, v36
	v_lshlrev_b64 v[28:29], 12, v[36:37]
	v_lshl_add_u64 v[28:29], s[98:99], 0, v[28:29]
	v_lshl_add_u64 v[38:39], v[28:29], 0, v[0:1]
	v_mov_b64_e32 v[28:29], v[140:141]
	v_mov_b64_e32 v[30:31], v[142:143]
	v_mov_b64_e32 v[44:45], v[196:197]
	v_mov_b64_e32 v[46:47], v[198:199]
	v_mov_b32_e32 v41, v22
	v_mov_b32_e32 v22, v43
	v_lshlrev_b32_e32 v38, 16, v28
	v_lshlrev_b32_e32 v39, 16, v44
	v_pk_mul_f32 v[38:39], v[48:49], v[38:39]
	s_nop 0
	v_add_f32_e32 v40, v38, v39
	v_and_b32_e32 v39, 0xffff0000, v44
	v_and_b32_e32 v38, 0xffff0000, v28
	v_pk_mul_f32 v[20:21], v[20:21], v[38:39]
	v_lshlrev_b32_e32 v39, 16, v45
	v_add_f32_e32 v20, v20, v21
	v_cvt_pk_bf16_f32 v20, v40, v20
	v_lshlrev_b32_e32 v38, 16, v29
	v_mov_b32_e32 v40, v42
	v_pk_mul_f32 v[38:39], v[40:41], v[38:39]
	v_mov_b32_e32 v28, v32
	v_add_f32_e32 v21, v38, v39
	v_and_b32_e32 v39, 0xffff0000, v45
	v_and_b32_e32 v38, 0xffff0000, v29
	v_pk_mul_f32 v[22:23], v[22:23], v[38:39]
	v_mov_b32_e32 v29, v12
	v_add_f32_e32 v22, v22, v23
	v_cvt_pk_bf16_f32 v21, v21, v22
	v_lshlrev_b32_e32 v23, 16, v46
	v_lshlrev_b32_e32 v22, 16, v30
	v_pk_mul_f32 v[22:23], v[28:29], v[22:23]
	v_mov_b32_e32 v12, v33
	v_add_f32_e32 v28, v22, v23
	v_and_b32_e32 v23, 0xffff0000, v46
	v_and_b32_e32 v22, 0xffff0000, v30
	v_pk_mul_f32 v[12:13], v[12:13], v[22:23]
	v_mov_b32_e32 v29, v14
	v_add_f32_e32 v12, v12, v13
	v_cvt_pk_bf16_f32 v22, v28, v12
	v_lshlrev_b32_e32 v13, 16, v47
	v_lshlrev_b32_e32 v12, 16, v31
	v_mov_b32_e32 v28, v34
	v_pk_mul_f32 v[12:13], v[28:29], v[12:13]
	v_mov_b32_e32 v14, v35
	v_add_f32_e32 v23, v12, v13
	v_and_b32_e32 v13, 0xffff0000, v47
	v_and_b32_e32 v12, 0xffff0000, v31
	v_pk_mul_f32 v[12:13], v[14:15], v[12:13]
	v_mov_b32_e32 v32, v24
	v_add_f32_e32 v12, v12, v13
	v_cvt_pk_bf16_f32 v23, v23, v12
	v_lshlrev_b64 v[12:13], 11, v[36:37]
	v_lshl_add_u64 v[12:13], s[62:63], 0, v[12:13]
	v_lshl_add_u64 v[12:13], v[12:13], 0, v[0:1]
	global_store_dwordx4 v[12:13], v[20:23], off
	v_mov_b32_e32 v33, v8
	v_mov_b32_e32 v8, v25
	v_add_u32_e32 v20, 0xb0, v116
	v_ashrrev_i32_e32 v21, 31, v20
	v_lshlrev_b64 v[12:13], 12, v[20:21]
	v_lshl_add_u64 v[12:13], s[98:99], 0, v[12:13]
	v_lshl_add_u64 v[22:23], v[12:13], 0, v[0:1]
	v_mov_b64_e32 v[12:13], v[200:201]
	v_mov_b64_e32 v[14:15], v[202:203]
	v_mov_b64_e32 v[28:29], v[208:209]
	v_mov_b64_e32 v[30:31], v[210:211]
	v_mov_b32_e32 v25, v10
	v_mov_b32_e32 v10, v27
	v_lshlrev_b32_e32 v22, 16, v12
	v_lshlrev_b32_e32 v23, 16, v28
	v_pk_mul_f32 v[22:23], v[32:33], v[22:23]
	s_nop 0
	v_add_f32_e32 v24, v22, v23
	v_and_b32_e32 v23, 0xffff0000, v28
	v_and_b32_e32 v22, 0xffff0000, v12
	v_pk_mul_f32 v[8:9], v[8:9], v[22:23]
	v_lshlrev_b32_e32 v23, 16, v29
	v_add_f32_e32 v8, v8, v9
	v_cvt_pk_bf16_f32 v8, v24, v8
	v_lshlrev_b32_e32 v22, 16, v13
	v_mov_b32_e32 v24, v26
	v_pk_mul_f32 v[22:23], v[24:25], v[22:23]
	v_mov_b32_e32 v12, v16
	v_add_f32_e32 v9, v22, v23
	v_and_b32_e32 v23, 0xffff0000, v29
	v_and_b32_e32 v22, 0xffff0000, v13
	v_pk_mul_f32 v[10:11], v[10:11], v[22:23]
	v_mov_b32_e32 v13, v4
	v_add_f32_e32 v10, v10, v11
	v_cvt_pk_bf16_f32 v9, v9, v10
	v_lshlrev_b32_e32 v11, 16, v30
	v_lshlrev_b32_e32 v10, 16, v14
	v_pk_mul_f32 v[10:11], v[12:13], v[10:11]
	v_mov_b32_e32 v4, v17
	v_add_f32_e32 v12, v10, v11
	v_and_b32_e32 v11, 0xffff0000, v30
	v_and_b32_e32 v10, 0xffff0000, v14
	v_pk_mul_f32 v[4:5], v[4:5], v[10:11]
	v_mov_b32_e32 v13, v6
	v_add_f32_e32 v4, v4, v5
	v_cvt_pk_bf16_f32 v10, v12, v4
	v_lshlrev_b32_e32 v5, 16, v31
	v_lshlrev_b32_e32 v4, 16, v15
	v_mov_b32_e32 v12, v18
	v_pk_mul_f32 v[4:5], v[12:13], v[4:5]
	v_mov_b32_e32 v6, v19
	v_add_f32_e32 v11, v4, v5
	v_and_b32_e32 v5, 0xffff0000, v31
	v_and_b32_e32 v4, 0xffff0000, v15
	v_pk_mul_f32 v[4:5], v[6:7], v[4:5]
	s_nop 0
	v_add_f32_e32 v4, v4, v5
	v_cvt_pk_bf16_f32 v11, v11, v4
	v_lshlrev_b64 v[4:5], 11, v[20:21]
	v_lshl_add_u64 v[4:5], s[62:63], 0, v[4:5]
	v_lshl_add_u64 v[0:1], v[4:5], 0, v[0:1]
	global_store_dwordx4 v[0:1], v[8:11], off
	s_cbranch_vccnz .LBB0_201
	s_andn2_b64 vcc, exec, s[66:67]
	s_cbranch_vccnz .LBB0_200
	s_barrier
	s_branch .LBB0_200
